# LRU pass C: carry-scan AGG loads issued at the start of the prologue (overlap with GW/raw loads and k8 math)
# speedup vs baseline: 1.0022x; 1.0022x over previous
.LBB0_579:
	s_andn2_b64 vcc, exec, s[0:1]
	s_cbranch_vccnz .LBB0_688
	s_and_b64 s[0:1], s[10:11], exec
	s_cselect_b32 s5, 0, 2
	v_readlane_b32 s0, v243, 57
	s_add_i32 s0, s5, s0
	s_cmpk_gt_i32 s0, 0x81
	v_mov_b32_e32 v0, v175
	s_mov_b64 s[58:59], s[68:69]
	v_readlane_b32 s1, v243, 58
	s_cbranch_scc1 .LBB0_621
	v_readlane_b32 s1, v243, 12
	s_lshl_b32 s1, s1, 1
	s_lshl_b32 s4, s96, 19
	s_or_b32 s1, s4, s1
	s_add_u32 s1, s58, s1
	s_addc_u32 s4, s59, 0
	s_add_u32 s6, s1, 0x15ee4c40
	s_addc_u32 s7, s4, 0
	v_ashrrev_i32_e32 v1, 31, v0
	v_lshl_add_u64 v[4:5], v[0:1], 4, s[6:7]
	s_barrier
	s_branch .Lcf_entry
.Lcf_ret1:
	global_load_dwordx4 v[48:51], v[4:5], off
	v_add_u32_e32 v8, 0x200, v0
	v_lshl_add_u32 v2, v0, 4, 0
	v_ashrrev_i32_e32 v9, 31, v8
	v_lshl_add_u64 v[4:5], v[8:9], 4, s[6:7]
	global_load_dwordx4 v[52:55], v[4:5], off
	v_add_u32_e32 v8, 0x400, v0
	v_ashrrev_i32_e32 v9, 31, v8
	v_lshl_add_u64 v[4:5], v[8:9], 4, s[6:7]
	global_load_dwordx4 v[56:59], v[4:5], off
	v_add_u32_e32 v8, 0x600, v0
	v_ashrrev_i32_e32 v9, 31, v8
	v_lshl_add_u64 v[4:5], v[8:9], 4, s[6:7]
	global_load_dwordx4 v[60:63], v[4:5], off
	v_lshlrev_b32_e32 v29, 4, v0
	v_lshlrev_b32_e32 v31, 2, v0
	s_movk_i32 s1, 0x140
	v_and_b32_e32 v3, 63, v0
	v_cmp_gt_i32_e32 vcc, s1, v0
	s_and_saveexec_b64 s[40:41], vcc
	s_cbranch_execz .LBB0_587
	v_ashrrev_i32_e32 v6, 6, v0
	v_cmp_lt_i32_e32 vcc, 3, v6
	s_and_saveexec_b64 s[6:7], vcc
	s_xor_b64 s[42:43], exec, s[6:7]
	s_cbranch_execz .LBB0_584
	s_lshl_b32 s1, s96, 10
	v_readlane_b32 s4, v243, 13
	s_or_b32 s1, s1, s4
	s_mov_b64 s[6:7], s[10:11]
	v_readlane_b32 s8, v243, 14
	v_or_b32_e32 v144, s1, v3
	v_readlane_b32 s10, v243, 16
	v_readlane_b32 s11, v243, 17
	v_readlane_b32 s9, v243, 15
	s_movk_i32 s31, 0x4100
	v_lshl_add_u64 v[4:5], v[144:145], 2, s[10:11]
	s_mov_b64 s[10:11], s[6:7]

.Lcf_var_0:
	s_add_u32 s100, s68, 0x16064c40
	s_addc_u32 s101, s69, 0
	global_load_dwordx2 v[120:121], v20, s[100:101] sc1
	s_add_u32 s100, s68, 0x16066c40
	s_addc_u32 s101, s69, 0
	global_load_dwordx2 v[122:123], v20, s[100:101] sc1
	s_add_u32 s100, s68, 0x16068c40
	s_addc_u32 s101, s69, 0
	global_load_dwordx2 v[124:125], v20, s[100:101] sc1
	s_add_u32 s100, s68, 0x1606ac40
	s_addc_u32 s101, s69, 0
	global_load_dwordx2 v[126:127], v20, s[100:101] sc1
	s_add_u32 s100, s68, 0x1606cc40
	s_addc_u32 s101, s69, 0
	global_load_dwordx2 v[128:129], v20, s[100:101] sc1
	s_add_u32 s100, s68, 0x1606ec40
	s_addc_u32 s101, s69, 0
	global_load_dwordx2 v[130:131], v20, s[100:101] sc1
	s_add_u32 s100, s68, 0x16070c40
	s_addc_u32 s101, s69, 0
	global_load_dwordx2 v[132:133], v20, s[100:101] sc1
	s_add_u32 s100, s68, 0x16072c40
	s_addc_u32 s101, s69, 0
	global_load_dwordx2 v[134:135], v20, s[100:101] sc1
	s_add_u32 s100, s68, 0x16074c40
	s_addc_u32 s101, s69, 0
	global_load_dwordx2 v[64:65], v20, s[100:101] sc1
	s_add_u32 s100, s68, 0x16076c40
	s_addc_u32 s101, s69, 0
	global_load_dwordx2 v[66:67], v20, s[100:101] sc1
	s_add_u32 s100, s68, 0x16078c40
	s_addc_u32 s101, s69, 0
	global_load_dwordx2 v[68:69], v20, s[100:101] sc1
	s_add_u32 s100, s68, 0x1607ac40
	s_addc_u32 s101, s69, 0
	global_load_dwordx2 v[70:71], v20, s[100:101] sc1
	s_add_u32 s100, s68, 0x1607cc40
	s_addc_u32 s101, s69, 0
	global_load_dwordx2 v[78:79], v20, s[100:101] sc1
	s_add_u32 s100, s68, 0x1607ec40
	s_addc_u32 s101, s69, 0
	global_load_dwordx2 v[80:81], v20, s[100:101] sc1
	s_add_u32 s100, s68, 0x16080c40
	s_addc_u32 s101, s69, 0
	global_load_dwordx2 v[82:83], v20, s[100:101] sc1
	s_add_u32 s100, s68, 0x16082c40
	s_addc_u32 s101, s69, 0
	global_load_dwordx2 v[84:85], v20, s[100:101] sc1
	s_add_u32 s100, s68, 0x16084c40
	s_addc_u32 s101, s69, 0
	global_load_dwordx2 v[86:87], v20, s[100:101] sc1
	s_add_u32 s100, s68, 0x16086c40
	s_addc_u32 s101, s69, 0
	global_load_dwordx2 v[88:89], v20, s[100:101] sc1
	s_add_u32 s100, s68, 0x16088c40
	s_addc_u32 s101, s69, 0
	global_load_dwordx2 v[90:91], v20, s[100:101] sc1
	s_add_u32 s100, s68, 0x1608ac40
	s_addc_u32 s101, s69, 0
	global_load_dwordx2 v[92:93], v20, s[100:101] sc1
	s_add_u32 s100, s68, 0x1608cc40
	s_addc_u32 s101, s69, 0
	global_load_dwordx2 v[94:95], v20, s[100:101] sc1
	s_add_u32 s100, s68, 0x1608ec40
	s_addc_u32 s101, s69, 0
	global_load_dwordx2 v[96:97], v20, s[100:101] sc1
	s_add_u32 s100, s68, 0x16090c40
	s_addc_u32 s101, s69, 0
	global_load_dwordx2 v[98:99], v20, s[100:101] sc1
	s_add_u32 s100, s68, 0x16092c40
	s_addc_u32 s101, s69, 0
	global_load_dwordx2 v[100:101], v20, s[100:101] sc1
	s_add_u32 s100, s68, 0x16094c40
	s_addc_u32 s101, s69, 0
	global_load_dwordx2 v[102:103], v20, s[100:101] sc1
	s_add_u32 s100, s68, 0x16096c40
	s_addc_u32 s101, s69, 0
	global_load_dwordx2 v[104:105], v20, s[100:101] sc1
	s_add_u32 s100, s68, 0x16098c40
	s_addc_u32 s101, s69, 0
	global_load_dwordx2 v[106:107], v20, s[100:101] sc1
	s_add_u32 s100, s68, 0x1609ac40
	s_addc_u32 s101, s69, 0
	global_load_dwordx2 v[108:109], v20, s[100:101] sc1
	s_add_u32 s100, s68, 0x1609cc40
	s_addc_u32 s101, s69, 0
	global_load_dwordx2 v[110:111], v20, s[100:101] sc1
	s_add_u32 s100, s68, 0x1609ec40
	s_addc_u32 s101, s69, 0
	global_load_dwordx2 v[112:113], v20, s[100:101] sc1
	s_add_u32 s100, s68, 0x160a0c40
	s_addc_u32 s101, s69, 0
	global_load_dwordx2 v[114:115], v20, s[100:101] sc1
	s_add_u32 s100, s68, 0x160a2c40
	s_addc_u32 s101, s69, 0
	global_load_dwordx2 v[116:117], v20, s[100:101] sc1
	s_add_u32 s100, s68, 0x160a4c40
	s_addc_u32 s101, s69, 0
	global_load_dwordx2 v[118:119], v20, s[100:101] sc1
	s_branch .Lcf_ret1
.Lcf_scan_0:
	v_mov_b32_e32 v24, 1.0
	v_mov_b32_e32 v25, 0
	s_waitcnt vmcnt(32)
	v_fma_f32 v25, v120, v25, v121
	v_mul_f32_e32 v24, v24, v120
	s_waitcnt vmcnt(31)
	v_fma_f32 v25, v122, v25, v123
	v_mul_f32_e32 v24, v24, v122
	s_waitcnt vmcnt(30)
	v_fma_f32 v25, v124, v25, v125
	v_mul_f32_e32 v24, v24, v124
	s_waitcnt vmcnt(29)
	v_fma_f32 v25, v126, v25, v127
	v_mul_f32_e32 v24, v24, v126
	s_waitcnt vmcnt(28)
	v_fma_f32 v25, v128, v25, v129
	v_mul_f32_e32 v24, v24, v128
	s_waitcnt vmcnt(27)
	v_fma_f32 v25, v130, v25, v131
	v_mul_f32_e32 v24, v24, v130
	s_waitcnt vmcnt(26)
	v_fma_f32 v25, v132, v25, v133
	v_mul_f32_e32 v24, v24, v132
	s_waitcnt vmcnt(25)
	v_fma_f32 v25, v134, v25, v135
	v_mul_f32_e32 v24, v24, v134
	s_waitcnt vmcnt(24)
	v_fma_f32 v25, v64, v25, v65
	v_mul_f32_e32 v24, v24, v64
	s_waitcnt vmcnt(23)
	v_fma_f32 v25, v66, v25, v67
	v_mul_f32_e32 v24, v24, v66
	s_waitcnt vmcnt(22)
	v_fma_f32 v25, v68, v25, v69
	v_mul_f32_e32 v24, v24, v68
	s_waitcnt vmcnt(21)
	v_fma_f32 v25, v70, v25, v71
	v_mul_f32_e32 v24, v24, v70
	s_waitcnt vmcnt(20)
	v_fma_f32 v25, v78, v25, v79
	v_mul_f32_e32 v24, v24, v78
	s_waitcnt vmcnt(19)
	v_fma_f32 v25, v80, v25, v81
	v_mul_f32_e32 v24, v24, v80
	s_waitcnt vmcnt(18)
	v_fma_f32 v25, v82, v25, v83
	v_mul_f32_e32 v24, v24, v82
	s_waitcnt vmcnt(17)
	v_fma_f32 v25, v84, v25, v85
	v_mul_f32_e32 v24, v24, v84
	s_waitcnt vmcnt(16)
	v_fma_f32 v25, v86, v25, v87
	v_mul_f32_e32 v24, v24, v86
	s_waitcnt vmcnt(15)
	v_fma_f32 v25, v88, v25, v89
	v_mul_f32_e32 v24, v24, v88
	s_waitcnt vmcnt(14)
	v_fma_f32 v25, v90, v25, v91
	v_mul_f32_e32 v24, v24, v90
	s_waitcnt vmcnt(13)
	v_fma_f32 v25, v92, v25, v93
	v_mul_f32_e32 v24, v24, v92
	s_waitcnt vmcnt(12)
	v_fma_f32 v25, v94, v25, v95
	v_mul_f32_e32 v24, v24, v94
	s_waitcnt vmcnt(11)
	v_fma_f32 v25, v96, v25, v97
	v_mul_f32_e32 v24, v24, v96
	s_waitcnt vmcnt(10)
	v_fma_f32 v25, v98, v25, v99
	v_mul_f32_e32 v24, v24, v98
	s_waitcnt vmcnt(9)
	v_fma_f32 v25, v100, v25, v101
	v_mul_f32_e32 v24, v24, v100
	s_waitcnt vmcnt(8)
	v_fma_f32 v25, v102, v25, v103
	v_mul_f32_e32 v24, v24, v102
	s_waitcnt vmcnt(7)
	v_fma_f32 v25, v104, v25, v105
	v_mul_f32_e32 v24, v24, v104
	s_waitcnt vmcnt(6)
	v_fma_f32 v25, v106, v25, v107
	v_mul_f32_e32 v24, v24, v106
	s_waitcnt vmcnt(5)
	v_fma_f32 v25, v108, v25, v109
	v_mul_f32_e32 v24, v24, v108
	s_waitcnt vmcnt(4)
	v_fma_f32 v25, v110, v25, v111
	v_mul_f32_e32 v24, v24, v110
	s_waitcnt vmcnt(3)
	v_fma_f32 v25, v112, v25, v113
	v_mul_f32_e32 v24, v24, v112
	s_waitcnt vmcnt(2)
	v_fma_f32 v25, v114, v25, v115
	v_mul_f32_e32 v24, v24, v114
	s_waitcnt vmcnt(1)
	v_fma_f32 v25, v116, v25, v117
	v_mul_f32_e32 v24, v24, v116
	s_waitcnt vmcnt(0)
	v_fma_f32 v25, v118, v25, v119
	v_mul_f32_e32 v24, v24, v118
	ds_write_b64 v22, v[24:25] offset:0
	s_waitcnt lgkmcnt(0)
	s_barrier
	v_mov_b32_e32 v26, 0
	s_cmp_eq_u32 s99, 0
	s_cbranch_scc0 .Lcf_skip_0_0
	s_add_u32 s100, s68, 0x1626cc40
	s_addc_u32 s101, s69, 0
	global_store_dword v21, v26, s[100:101]
.Lcf_skip_0_0:
	v_fma_f32 v26, v120, v26, v121
	s_cmp_eq_u32 s99, 1
	s_cbranch_scc0 .Lcf_skip_0_1
	s_add_u32 s100, s68, 0x1626dc40
	s_addc_u32 s101, s69, 0
	global_store_dword v21, v26, s[100:101]
.Lcf_skip_0_1:
	v_fma_f32 v26, v122, v26, v123
	s_cmp_eq_u32 s99, 2
	s_cbranch_scc0 .Lcf_skip_0_2
	s_add_u32 s100, s68, 0x1626ec40
	s_addc_u32 s101, s69, 0
	global_store_dword v21, v26, s[100:101]
.Lcf_skip_0_2:
	v_fma_f32 v26, v124, v26, v125
	s_cmp_eq_u32 s99, 3
	s_cbranch_scc0 .Lcf_skip_0_3
	s_add_u32 s100, s68, 0x1626fc40
	s_addc_u32 s101, s69, 0
	global_store_dword v21, v26, s[100:101]
.Lcf_skip_0_3:
	v_fma_f32 v26, v126, v26, v127
	s_cmp_eq_u32 s99, 4
	s_cbranch_scc0 .Lcf_skip_0_4
	s_add_u32 s100, s68, 0x16270c40
	s_addc_u32 s101, s69, 0
	global_store_dword v21, v26, s[100:101]
.Lcf_skip_0_4:
	v_fma_f32 v26, v128, v26, v129
	s_cmp_eq_u32 s99, 5
	s_cbranch_scc0 .Lcf_skip_0_5
	s_add_u32 s100, s68, 0x16271c40
	s_addc_u32 s101, s69, 0
	global_store_dword v21, v26, s[100:101]
.Lcf_skip_0_5:
	v_fma_f32 v26, v130, v26, v131
	s_cmp_eq_u32 s99, 6
	s_cbranch_scc0 .Lcf_skip_0_6
	s_add_u32 s100, s68, 0x16272c40
	s_addc_u32 s101, s69, 0
	global_store_dword v21, v26, s[100:101]
.Lcf_skip_0_6:
	v_fma_f32 v26, v132, v26, v133
	s_cmp_eq_u32 s99, 7
	s_cbranch_scc0 .Lcf_skip_0_7
	s_add_u32 s100, s68, 0x16273c40
	s_addc_u32 s101, s69, 0
	global_store_dword v21, v26, s[100:101]
.Lcf_skip_0_7:
	v_fma_f32 v26, v134, v26, v135
	s_cmp_eq_u32 s99, 8
	s_cbranch_scc0 .Lcf_skip_0_8
	s_add_u32 s100, s68, 0x16274c40
	s_addc_u32 s101, s69, 0
	global_store_dword v21, v26, s[100:101]

.Lcf_var_1:
	s_add_u32 s100, s68, 0x160a6c40
	s_addc_u32 s101, s69, 0
	global_load_dwordx2 v[120:121], v20, s[100:101] sc1
	s_add_u32 s100, s68, 0x160a8c40
	s_addc_u32 s101, s69, 0
	global_load_dwordx2 v[122:123], v20, s[100:101] sc1
	s_add_u32 s100, s68, 0x160aac40
	s_addc_u32 s101, s69, 0
	global_load_dwordx2 v[124:125], v20, s[100:101] sc1
	s_add_u32 s100, s68, 0x160acc40
	s_addc_u32 s101, s69, 0
	global_load_dwordx2 v[126:127], v20, s[100:101] sc1
	s_add_u32 s100, s68, 0x160aec40
	s_addc_u32 s101, s69, 0
	global_load_dwordx2 v[128:129], v20, s[100:101] sc1
	s_add_u32 s100, s68, 0x160b0c40
	s_addc_u32 s101, s69, 0
	global_load_dwordx2 v[130:131], v20, s[100:101] sc1
	s_add_u32 s100, s68, 0x160b2c40
	s_addc_u32 s101, s69, 0
	global_load_dwordx2 v[132:133], v20, s[100:101] sc1
	s_add_u32 s100, s68, 0x160b4c40
	s_addc_u32 s101, s69, 0
	global_load_dwordx2 v[134:135], v20, s[100:101] sc1
	s_add_u32 s100, s68, 0x160b6c40
	s_addc_u32 s101, s69, 0
	global_load_dwordx2 v[64:65], v20, s[100:101] sc1
	s_add_u32 s100, s68, 0x160b8c40
	s_addc_u32 s101, s69, 0
	global_load_dwordx2 v[66:67], v20, s[100:101] sc1
	s_add_u32 s100, s68, 0x160bac40
	s_addc_u32 s101, s69, 0
	global_load_dwordx2 v[68:69], v20, s[100:101] sc1
	s_add_u32 s100, s68, 0x160bcc40
	s_addc_u32 s101, s69, 0
	global_load_dwordx2 v[70:71], v20, s[100:101] sc1
	s_add_u32 s100, s68, 0x160bec40
	s_addc_u32 s101, s69, 0
	global_load_dwordx2 v[78:79], v20, s[100:101] sc1
	s_add_u32 s100, s68, 0x160c0c40
	s_addc_u32 s101, s69, 0
	global_load_dwordx2 v[80:81], v20, s[100:101] sc1
	s_add_u32 s100, s68, 0x160c2c40
	s_addc_u32 s101, s69, 0
	global_load_dwordx2 v[82:83], v20, s[100:101] sc1
	s_add_u32 s100, s68, 0x160c4c40
	s_addc_u32 s101, s69, 0
	global_load_dwordx2 v[84:85], v20, s[100:101] sc1
	s_add_u32 s100, s68, 0x160c6c40
	s_addc_u32 s101, s69, 0
	global_load_dwordx2 v[86:87], v20, s[100:101] sc1
	s_add_u32 s100, s68, 0x160c8c40
	s_addc_u32 s101, s69, 0
	global_load_dwordx2 v[88:89], v20, s[100:101] sc1
	s_add_u32 s100, s68, 0x160cac40
	s_addc_u32 s101, s69, 0
	global_load_dwordx2 v[90:91], v20, s[100:101] sc1
	s_add_u32 s100, s68, 0x160ccc40
	s_addc_u32 s101, s69, 0
	global_load_dwordx2 v[92:93], v20, s[100:101] sc1
	s_add_u32 s100, s68, 0x160cec40
	s_addc_u32 s101, s69, 0
	global_load_dwordx2 v[94:95], v20, s[100:101] sc1
	s_add_u32 s100, s68, 0x160d0c40
	s_addc_u32 s101, s69, 0
	global_load_dwordx2 v[96:97], v20, s[100:101] sc1
	s_add_u32 s100, s68, 0x160d2c40
	s_addc_u32 s101, s69, 0
	global_load_dwordx2 v[98:99], v20, s[100:101] sc1
	s_add_u32 s100, s68, 0x160d4c40
	s_addc_u32 s101, s69, 0
	global_load_dwordx2 v[100:101], v20, s[100:101] sc1
	s_add_u32 s100, s68, 0x160d6c40
	s_addc_u32 s101, s69, 0
	global_load_dwordx2 v[102:103], v20, s[100:101] sc1
	s_add_u32 s100, s68, 0x160d8c40
	s_addc_u32 s101, s69, 0
	global_load_dwordx2 v[104:105], v20, s[100:101] sc1
	s_add_u32 s100, s68, 0x160dac40
	s_addc_u32 s101, s69, 0
	global_load_dwordx2 v[106:107], v20, s[100:101] sc1
	s_add_u32 s100, s68, 0x160dcc40
	s_addc_u32 s101, s69, 0
	global_load_dwordx2 v[108:109], v20, s[100:101] sc1
	s_add_u32 s100, s68, 0x160dec40
	s_addc_u32 s101, s69, 0
	global_load_dwordx2 v[110:111], v20, s[100:101] sc1
	s_add_u32 s100, s68, 0x160e0c40
	s_addc_u32 s101, s69, 0
	global_load_dwordx2 v[112:113], v20, s[100:101] sc1
	s_add_u32 s100, s68, 0x160e2c40
	s_addc_u32 s101, s69, 0
	global_load_dwordx2 v[114:115], v20, s[100:101] sc1
	s_add_u32 s100, s68, 0x160e4c40
	s_addc_u32 s101, s69, 0
	global_load_dwordx2 v[116:117], v20, s[100:101] sc1
	s_add_u32 s100, s68, 0x160e6c40
	s_addc_u32 s101, s69, 0
	global_load_dwordx2 v[118:119], v20, s[100:101] sc1
	s_branch .Lcf_ret1
.Lcf_scan_1:
	v_mov_b32_e32 v24, 1.0
	v_mov_b32_e32 v25, 0
	s_waitcnt vmcnt(32)
	v_fma_f32 v25, v120, v25, v121
	v_mul_f32_e32 v24, v24, v120
	s_waitcnt vmcnt(31)
	v_fma_f32 v25, v122, v25, v123
	v_mul_f32_e32 v24, v24, v122
	s_waitcnt vmcnt(30)
	v_fma_f32 v25, v124, v25, v125
	v_mul_f32_e32 v24, v24, v124
	s_waitcnt vmcnt(29)
	v_fma_f32 v25, v126, v25, v127
	v_mul_f32_e32 v24, v24, v126
	s_waitcnt vmcnt(28)
	v_fma_f32 v25, v128, v25, v129
	v_mul_f32_e32 v24, v24, v128
	s_waitcnt vmcnt(27)
	v_fma_f32 v25, v130, v25, v131
	v_mul_f32_e32 v24, v24, v130
	s_waitcnt vmcnt(26)
	v_fma_f32 v25, v132, v25, v133
	v_mul_f32_e32 v24, v24, v132
	s_waitcnt vmcnt(25)
	v_fma_f32 v25, v134, v25, v135
	v_mul_f32_e32 v24, v24, v134
	s_waitcnt vmcnt(24)
	v_fma_f32 v25, v64, v25, v65
	v_mul_f32_e32 v24, v24, v64
	s_waitcnt vmcnt(23)
	v_fma_f32 v25, v66, v25, v67
	v_mul_f32_e32 v24, v24, v66
	s_waitcnt vmcnt(22)
	v_fma_f32 v25, v68, v25, v69
	v_mul_f32_e32 v24, v24, v68
	s_waitcnt vmcnt(21)
	v_fma_f32 v25, v70, v25, v71
	v_mul_f32_e32 v24, v24, v70
	s_waitcnt vmcnt(20)
	v_fma_f32 v25, v78, v25, v79
	v_mul_f32_e32 v24, v24, v78
	s_waitcnt vmcnt(19)
	v_fma_f32 v25, v80, v25, v81
	v_mul_f32_e32 v24, v24, v80
	s_waitcnt vmcnt(18)
	v_fma_f32 v25, v82, v25, v83
	v_mul_f32_e32 v24, v24, v82
	s_waitcnt vmcnt(17)
	v_fma_f32 v25, v84, v25, v85
	v_mul_f32_e32 v24, v24, v84
	s_waitcnt vmcnt(16)
	v_fma_f32 v25, v86, v25, v87
	v_mul_f32_e32 v24, v24, v86
	s_waitcnt vmcnt(15)
	v_fma_f32 v25, v88, v25, v89
	v_mul_f32_e32 v24, v24, v88
	s_waitcnt vmcnt(14)
	v_fma_f32 v25, v90, v25, v91
	v_mul_f32_e32 v24, v24, v90
	s_waitcnt vmcnt(13)
	v_fma_f32 v25, v92, v25, v93
	v_mul_f32_e32 v24, v24, v92
	s_waitcnt vmcnt(12)
	v_fma_f32 v25, v94, v25, v95
	v_mul_f32_e32 v24, v24, v94
	s_waitcnt vmcnt(11)
	v_fma_f32 v25, v96, v25, v97
	v_mul_f32_e32 v24, v24, v96
	s_waitcnt vmcnt(10)
	v_fma_f32 v25, v98, v25, v99
	v_mul_f32_e32 v24, v24, v98
	s_waitcnt vmcnt(9)
	v_fma_f32 v25, v100, v25, v101
	v_mul_f32_e32 v24, v24, v100
	s_waitcnt vmcnt(8)
	v_fma_f32 v25, v102, v25, v103
	v_mul_f32_e32 v24, v24, v102
	s_waitcnt vmcnt(7)
	v_fma_f32 v25, v104, v25, v105
	v_mul_f32_e32 v24, v24, v104
	s_waitcnt vmcnt(6)
	v_fma_f32 v25, v106, v25, v107
	v_mul_f32_e32 v24, v24, v106
	s_waitcnt vmcnt(5)
	v_fma_f32 v25, v108, v25, v109
	v_mul_f32_e32 v24, v24, v108
	s_waitcnt vmcnt(4)
	v_fma_f32 v25, v110, v25, v111
	v_mul_f32_e32 v24, v24, v110
	s_waitcnt vmcnt(3)
	v_fma_f32 v25, v112, v25, v113
	v_mul_f32_e32 v24, v24, v112
	s_waitcnt vmcnt(2)
	v_fma_f32 v25, v114, v25, v115
	v_mul_f32_e32 v24, v24, v114
	s_waitcnt vmcnt(1)
	v_fma_f32 v25, v116, v25, v117
	v_mul_f32_e32 v24, v24, v116
	s_waitcnt vmcnt(0)
	v_fma_f32 v25, v118, v25, v119
	v_mul_f32_e32 v24, v24, v118
	ds_write_b64 v22, v[24:25] offset:512
	s_waitcnt lgkmcnt(0)
	s_barrier
	v_mov_b32_e32 v26, 0
	ds_read_b64 v[28:29], v22 offset:0
	s_waitcnt lgkmcnt(0)
	v_fma_f32 v26, v28, v26, v29
	s_cmp_eq_u32 s99, 1
	s_cbranch_scc0 .Lcf_skip_1_0
	s_add_u32 s100, s68, 0x1628dc40
	s_addc_u32 s101, s69, 0
	global_store_dword v21, v26, s[100:101]
.Lcf_skip_1_0:
	v_fma_f32 v26, v120, v26, v121
	s_cmp_eq_u32 s99, 2
	s_cbranch_scc0 .Lcf_skip_1_1
	s_add_u32 s100, s68, 0x1628ec40
	s_addc_u32 s101, s69, 0
	global_store_dword v21, v26, s[100:101]
.Lcf_skip_1_1:
	v_fma_f32 v26, v122, v26, v123
	s_cmp_eq_u32 s99, 3
	s_cbranch_scc0 .Lcf_skip_1_2
	s_add_u32 s100, s68, 0x1628fc40
	s_addc_u32 s101, s69, 0
	global_store_dword v21, v26, s[100:101]
.Lcf_skip_1_2:
	v_fma_f32 v26, v124, v26, v125
	s_cmp_eq_u32 s99, 4
	s_cbranch_scc0 .Lcf_skip_1_3
	s_add_u32 s100, s68, 0x16290c40
	s_addc_u32 s101, s69, 0
	global_store_dword v21, v26, s[100:101]
.Lcf_skip_1_3:
	v_fma_f32 v26, v126, v26, v127
	s_cmp_eq_u32 s99, 5
	s_cbranch_scc0 .Lcf_skip_1_4
	s_add_u32 s100, s68, 0x16291c40
	s_addc_u32 s101, s69, 0
	global_store_dword v21, v26, s[100:101]
.Lcf_skip_1_4:
	v_fma_f32 v26, v128, v26, v129
	s_cmp_eq_u32 s99, 6
	s_cbranch_scc0 .Lcf_skip_1_5
	s_add_u32 s100, s68, 0x16292c40
	s_addc_u32 s101, s69, 0
	global_store_dword v21, v26, s[100:101]
.Lcf_skip_1_5:
	v_fma_f32 v26, v130, v26, v131
	s_cmp_eq_u32 s99, 7
	s_cbranch_scc0 .Lcf_skip_1_6
	s_add_u32 s100, s68, 0x16293c40
	s_addc_u32 s101, s69, 0
	global_store_dword v21, v26, s[100:101]
.Lcf_skip_1_6:
	v_fma_f32 v26, v132, v26, v133
	s_cmp_eq_u32 s99, 8
	s_cbranch_scc0 .Lcf_skip_1_7
	s_add_u32 s100, s68, 0x16294c40
	s_addc_u32 s101, s69, 0
	global_store_dword v21, v26, s[100:101]
.Lcf_skip_1_7:
	v_fma_f32 v26, v134, v26, v135
	s_cmp_eq_u32 s99, 9
	s_cbranch_scc0 .Lcf_skip_1_8
	s_add_u32 s100, s68, 0x16295c40
	s_addc_u32 s101, s69, 0
	global_store_dword v21, v26, s[100:101]

.Lcf_var_2:
	s_add_u32 s100, s68, 0x160e8c40
	s_addc_u32 s101, s69, 0
	global_load_dwordx2 v[120:121], v20, s[100:101] sc1
	s_add_u32 s100, s68, 0x160eac40
	s_addc_u32 s101, s69, 0
	global_load_dwordx2 v[122:123], v20, s[100:101] sc1
	s_add_u32 s100, s68, 0x160ecc40
	s_addc_u32 s101, s69, 0
	global_load_dwordx2 v[124:125], v20, s[100:101] sc1
	s_add_u32 s100, s68, 0x160eec40
	s_addc_u32 s101, s69, 0
	global_load_dwordx2 v[126:127], v20, s[100:101] sc1
	s_add_u32 s100, s68, 0x160f0c40
	s_addc_u32 s101, s69, 0
	global_load_dwordx2 v[128:129], v20, s[100:101] sc1
	s_add_u32 s100, s68, 0x160f2c40
	s_addc_u32 s101, s69, 0
	global_load_dwordx2 v[130:131], v20, s[100:101] sc1
	s_add_u32 s100, s68, 0x160f4c40
	s_addc_u32 s101, s69, 0
	global_load_dwordx2 v[132:133], v20, s[100:101] sc1
	s_add_u32 s100, s68, 0x160f6c40
	s_addc_u32 s101, s69, 0
	global_load_dwordx2 v[134:135], v20, s[100:101] sc1
	s_add_u32 s100, s68, 0x160f8c40
	s_addc_u32 s101, s69, 0
	global_load_dwordx2 v[64:65], v20, s[100:101] sc1
	s_add_u32 s100, s68, 0x160fac40
	s_addc_u32 s101, s69, 0
	global_load_dwordx2 v[66:67], v20, s[100:101] sc1
	s_add_u32 s100, s68, 0x160fcc40
	s_addc_u32 s101, s69, 0
	global_load_dwordx2 v[68:69], v20, s[100:101] sc1
	s_add_u32 s100, s68, 0x160fec40
	s_addc_u32 s101, s69, 0
	global_load_dwordx2 v[70:71], v20, s[100:101] sc1
	s_add_u32 s100, s68, 0x16100c40
	s_addc_u32 s101, s69, 0
	global_load_dwordx2 v[78:79], v20, s[100:101] sc1
	s_add_u32 s100, s68, 0x16102c40
	s_addc_u32 s101, s69, 0
	global_load_dwordx2 v[80:81], v20, s[100:101] sc1
	s_add_u32 s100, s68, 0x16104c40
	s_addc_u32 s101, s69, 0
	global_load_dwordx2 v[82:83], v20, s[100:101] sc1
	s_add_u32 s100, s68, 0x16106c40
	s_addc_u32 s101, s69, 0
	global_load_dwordx2 v[84:85], v20, s[100:101] sc1
	s_add_u32 s100, s68, 0x16108c40
	s_addc_u32 s101, s69, 0
	global_load_dwordx2 v[86:87], v20, s[100:101] sc1
	s_add_u32 s100, s68, 0x1610ac40
	s_addc_u32 s101, s69, 0
	global_load_dwordx2 v[88:89], v20, s[100:101] sc1
	s_add_u32 s100, s68, 0x1610cc40
	s_addc_u32 s101, s69, 0
	global_load_dwordx2 v[90:91], v20, s[100:101] sc1
	s_add_u32 s100, s68, 0x1610ec40
	s_addc_u32 s101, s69, 0
	global_load_dwordx2 v[92:93], v20, s[100:101] sc1
	s_add_u32 s100, s68, 0x16110c40
	s_addc_u32 s101, s69, 0
	global_load_dwordx2 v[94:95], v20, s[100:101] sc1
	s_add_u32 s100, s68, 0x16112c40
	s_addc_u32 s101, s69, 0
	global_load_dwordx2 v[96:97], v20, s[100:101] sc1
	s_add_u32 s100, s68, 0x16114c40
	s_addc_u32 s101, s69, 0
	global_load_dwordx2 v[98:99], v20, s[100:101] sc1
	s_add_u32 s100, s68, 0x16116c40
	s_addc_u32 s101, s69, 0
	global_load_dwordx2 v[100:101], v20, s[100:101] sc1
	s_add_u32 s100, s68, 0x16118c40
	s_addc_u32 s101, s69, 0
	global_load_dwordx2 v[102:103], v20, s[100:101] sc1
	s_add_u32 s100, s68, 0x1611ac40
	s_addc_u32 s101, s69, 0
	global_load_dwordx2 v[104:105], v20, s[100:101] sc1
	s_add_u32 s100, s68, 0x1611cc40
	s_addc_u32 s101, s69, 0
	global_load_dwordx2 v[106:107], v20, s[100:101] sc1
	s_add_u32 s100, s68, 0x1611ec40
	s_addc_u32 s101, s69, 0
	global_load_dwordx2 v[108:109], v20, s[100:101] sc1
	s_add_u32 s100, s68, 0x16120c40
	s_addc_u32 s101, s69, 0
	global_load_dwordx2 v[110:111], v20, s[100:101] sc1
	s_add_u32 s100, s68, 0x16122c40
	s_addc_u32 s101, s69, 0
	global_load_dwordx2 v[112:113], v20, s[100:101] sc1
	s_add_u32 s100, s68, 0x16124c40
	s_addc_u32 s101, s69, 0
	global_load_dwordx2 v[114:115], v20, s[100:101] sc1
	s_add_u32 s100, s68, 0x16126c40
	s_addc_u32 s101, s69, 0
	global_load_dwordx2 v[116:117], v20, s[100:101] sc1
	s_add_u32 s100, s68, 0x16128c40
	s_addc_u32 s101, s69, 0
	global_load_dwordx2 v[118:119], v20, s[100:101] sc1
	s_branch .Lcf_ret1
.Lcf_scan_2:
	v_mov_b32_e32 v24, 1.0
	v_mov_b32_e32 v25, 0
	s_waitcnt vmcnt(32)
	v_fma_f32 v25, v120, v25, v121
	v_mul_f32_e32 v24, v24, v120
	s_waitcnt vmcnt(31)
	v_fma_f32 v25, v122, v25, v123
	v_mul_f32_e32 v24, v24, v122
	s_waitcnt vmcnt(30)
	v_fma_f32 v25, v124, v25, v125
	v_mul_f32_e32 v24, v24, v124
	s_waitcnt vmcnt(29)
	v_fma_f32 v25, v126, v25, v127
	v_mul_f32_e32 v24, v24, v126
	s_waitcnt vmcnt(28)
	v_fma_f32 v25, v128, v25, v129
	v_mul_f32_e32 v24, v24, v128
	s_waitcnt vmcnt(27)
	v_fma_f32 v25, v130, v25, v131
	v_mul_f32_e32 v24, v24, v130
	s_waitcnt vmcnt(26)
	v_fma_f32 v25, v132, v25, v133
	v_mul_f32_e32 v24, v24, v132
	s_waitcnt vmcnt(25)
	v_fma_f32 v25, v134, v25, v135
	v_mul_f32_e32 v24, v24, v134
	s_waitcnt vmcnt(24)
	v_fma_f32 v25, v64, v25, v65
	v_mul_f32_e32 v24, v24, v64
	s_waitcnt vmcnt(23)
	v_fma_f32 v25, v66, v25, v67
	v_mul_f32_e32 v24, v24, v66
	s_waitcnt vmcnt(22)
	v_fma_f32 v25, v68, v25, v69
	v_mul_f32_e32 v24, v24, v68
	s_waitcnt vmcnt(21)
	v_fma_f32 v25, v70, v25, v71
	v_mul_f32_e32 v24, v24, v70
	s_waitcnt vmcnt(20)
	v_fma_f32 v25, v78, v25, v79
	v_mul_f32_e32 v24, v24, v78
	s_waitcnt vmcnt(19)
	v_fma_f32 v25, v80, v25, v81
	v_mul_f32_e32 v24, v24, v80
	s_waitcnt vmcnt(18)
	v_fma_f32 v25, v82, v25, v83
	v_mul_f32_e32 v24, v24, v82
	s_waitcnt vmcnt(17)
	v_fma_f32 v25, v84, v25, v85
	v_mul_f32_e32 v24, v24, v84
	s_waitcnt vmcnt(16)
	v_fma_f32 v25, v86, v25, v87
	v_mul_f32_e32 v24, v24, v86
	s_waitcnt vmcnt(15)
	v_fma_f32 v25, v88, v25, v89
	v_mul_f32_e32 v24, v24, v88
	s_waitcnt vmcnt(14)
	v_fma_f32 v25, v90, v25, v91
	v_mul_f32_e32 v24, v24, v90
	s_waitcnt vmcnt(13)
	v_fma_f32 v25, v92, v25, v93
	v_mul_f32_e32 v24, v24, v92
	s_waitcnt vmcnt(12)
	v_fma_f32 v25, v94, v25, v95
	v_mul_f32_e32 v24, v24, v94
	s_waitcnt vmcnt(11)
	v_fma_f32 v25, v96, v25, v97
	v_mul_f32_e32 v24, v24, v96
	s_waitcnt vmcnt(10)
	v_fma_f32 v25, v98, v25, v99
	v_mul_f32_e32 v24, v24, v98
	s_waitcnt vmcnt(9)
	v_fma_f32 v25, v100, v25, v101
	v_mul_f32_e32 v24, v24, v100
	s_waitcnt vmcnt(8)
	v_fma_f32 v25, v102, v25, v103
	v_mul_f32_e32 v24, v24, v102
	s_waitcnt vmcnt(7)
	v_fma_f32 v25, v104, v25, v105
	v_mul_f32_e32 v24, v24, v104
	s_waitcnt vmcnt(6)
	v_fma_f32 v25, v106, v25, v107
	v_mul_f32_e32 v24, v24, v106
	s_waitcnt vmcnt(5)
	v_fma_f32 v25, v108, v25, v109
	v_mul_f32_e32 v24, v24, v108
	s_waitcnt vmcnt(4)
	v_fma_f32 v25, v110, v25, v111
	v_mul_f32_e32 v24, v24, v110
	s_waitcnt vmcnt(3)
	v_fma_f32 v25, v112, v25, v113
	v_mul_f32_e32 v24, v24, v112
	s_waitcnt vmcnt(2)
	v_fma_f32 v25, v114, v25, v115
	v_mul_f32_e32 v24, v24, v114
	s_waitcnt vmcnt(1)
	v_fma_f32 v25, v116, v25, v117
	v_mul_f32_e32 v24, v24, v116
	s_waitcnt vmcnt(0)
	v_fma_f32 v25, v118, v25, v119
	v_mul_f32_e32 v24, v24, v118
	ds_write_b64 v22, v[24:25] offset:1024
	s_waitcnt lgkmcnt(0)
	s_barrier
	v_mov_b32_e32 v26, 0
	ds_read_b64 v[28:29], v22 offset:0
	s_waitcnt lgkmcnt(0)
	v_fma_f32 v26, v28, v26, v29
	ds_read_b64 v[28:29], v22 offset:512
	s_waitcnt lgkmcnt(0)
	v_fma_f32 v26, v28, v26, v29
	s_cmp_eq_u32 s99, 2
	s_cbranch_scc0 .Lcf_skip_2_0
	s_add_u32 s100, s68, 0x162aec40
	s_addc_u32 s101, s69, 0
	global_store_dword v21, v26, s[100:101]
.Lcf_skip_2_0:
	v_fma_f32 v26, v120, v26, v121
	s_cmp_eq_u32 s99, 3
	s_cbranch_scc0 .Lcf_skip_2_1
	s_add_u32 s100, s68, 0x162afc40
	s_addc_u32 s101, s69, 0
	global_store_dword v21, v26, s[100:101]
.Lcf_skip_2_1:
	v_fma_f32 v26, v122, v26, v123
	s_cmp_eq_u32 s99, 4
	s_cbranch_scc0 .Lcf_skip_2_2
	s_add_u32 s100, s68, 0x162b0c40
	s_addc_u32 s101, s69, 0
	global_store_dword v21, v26, s[100:101]
.Lcf_skip_2_2:
	v_fma_f32 v26, v124, v26, v125
	s_cmp_eq_u32 s99, 5
	s_cbranch_scc0 .Lcf_skip_2_3
	s_add_u32 s100, s68, 0x162b1c40
	s_addc_u32 s101, s69, 0
	global_store_dword v21, v26, s[100:101]
.Lcf_skip_2_3:
	v_fma_f32 v26, v126, v26, v127
	s_cmp_eq_u32 s99, 6
	s_cbranch_scc0 .Lcf_skip_2_4
	s_add_u32 s100, s68, 0x162b2c40
	s_addc_u32 s101, s69, 0
	global_store_dword v21, v26, s[100:101]
.Lcf_skip_2_4:
	v_fma_f32 v26, v128, v26, v129
	s_cmp_eq_u32 s99, 7
	s_cbranch_scc0 .Lcf_skip_2_5
	s_add_u32 s100, s68, 0x162b3c40
	s_addc_u32 s101, s69, 0
	global_store_dword v21, v26, s[100:101]
.Lcf_skip_2_5:
	v_fma_f32 v26, v130, v26, v131
	s_cmp_eq_u32 s99, 8
	s_cbranch_scc0 .Lcf_skip_2_6
	s_add_u32 s100, s68, 0x162b4c40
	s_addc_u32 s101, s69, 0
	global_store_dword v21, v26, s[100:101]
.Lcf_skip_2_6:
	v_fma_f32 v26, v132, v26, v133
	s_cmp_eq_u32 s99, 9
	s_cbranch_scc0 .Lcf_skip_2_7
	s_add_u32 s100, s68, 0x162b5c40
	s_addc_u32 s101, s69, 0
	global_store_dword v21, v26, s[100:101]
.Lcf_skip_2_7:
	v_fma_f32 v26, v134, v26, v135
	s_cmp_eq_u32 s99, 10
	s_cbranch_scc0 .Lcf_skip_2_8
	s_add_u32 s100, s68, 0x162b6c40
	s_addc_u32 s101, s69, 0
	global_store_dword v21, v26, s[100:101]

.Lcf_var_3:
	s_add_u32 s100, s68, 0x1612ac40
	s_addc_u32 s101, s69, 0
	global_load_dwordx2 v[120:121], v20, s[100:101] sc1
	s_add_u32 s100, s68, 0x1612cc40
	s_addc_u32 s101, s69, 0
	global_load_dwordx2 v[122:123], v20, s[100:101] sc1
	s_add_u32 s100, s68, 0x1612ec40
	s_addc_u32 s101, s69, 0
	global_load_dwordx2 v[124:125], v20, s[100:101] sc1
	s_add_u32 s100, s68, 0x16130c40
	s_addc_u32 s101, s69, 0
	global_load_dwordx2 v[126:127], v20, s[100:101] sc1
	s_add_u32 s100, s68, 0x16132c40
	s_addc_u32 s101, s69, 0
	global_load_dwordx2 v[128:129], v20, s[100:101] sc1
	s_add_u32 s100, s68, 0x16134c40
	s_addc_u32 s101, s69, 0
	global_load_dwordx2 v[130:131], v20, s[100:101] sc1
	s_add_u32 s100, s68, 0x16136c40
	s_addc_u32 s101, s69, 0
	global_load_dwordx2 v[132:133], v20, s[100:101] sc1
	s_add_u32 s100, s68, 0x16138c40
	s_addc_u32 s101, s69, 0
	global_load_dwordx2 v[134:135], v20, s[100:101] sc1
	s_add_u32 s100, s68, 0x1613ac40
	s_addc_u32 s101, s69, 0
	global_load_dwordx2 v[64:65], v20, s[100:101] sc1
	s_add_u32 s100, s68, 0x1613cc40
	s_addc_u32 s101, s69, 0
	global_load_dwordx2 v[66:67], v20, s[100:101] sc1
	s_add_u32 s100, s68, 0x1613ec40
	s_addc_u32 s101, s69, 0
	global_load_dwordx2 v[68:69], v20, s[100:101] sc1
	s_add_u32 s100, s68, 0x16140c40
	s_addc_u32 s101, s69, 0
	global_load_dwordx2 v[70:71], v20, s[100:101] sc1
	s_add_u32 s100, s68, 0x16142c40
	s_addc_u32 s101, s69, 0
	global_load_dwordx2 v[78:79], v20, s[100:101] sc1
	s_add_u32 s100, s68, 0x16144c40
	s_addc_u32 s101, s69, 0
	global_load_dwordx2 v[80:81], v20, s[100:101] sc1
	s_add_u32 s100, s68, 0x16146c40
	s_addc_u32 s101, s69, 0
	global_load_dwordx2 v[82:83], v20, s[100:101] sc1
	s_add_u32 s100, s68, 0x16148c40
	s_addc_u32 s101, s69, 0
	global_load_dwordx2 v[84:85], v20, s[100:101] sc1
	s_add_u32 s100, s68, 0x1614ac40
	s_addc_u32 s101, s69, 0
	global_load_dwordx2 v[86:87], v20, s[100:101] sc1
	s_add_u32 s100, s68, 0x1614cc40
	s_addc_u32 s101, s69, 0
	global_load_dwordx2 v[88:89], v20, s[100:101] sc1
	s_add_u32 s100, s68, 0x1614ec40
	s_addc_u32 s101, s69, 0
	global_load_dwordx2 v[90:91], v20, s[100:101] sc1
	s_add_u32 s100, s68, 0x16150c40
	s_addc_u32 s101, s69, 0
	global_load_dwordx2 v[92:93], v20, s[100:101] sc1
	s_add_u32 s100, s68, 0x16152c40
	s_addc_u32 s101, s69, 0
	global_load_dwordx2 v[94:95], v20, s[100:101] sc1
	s_add_u32 s100, s68, 0x16154c40
	s_addc_u32 s101, s69, 0
	global_load_dwordx2 v[96:97], v20, s[100:101] sc1
	s_add_u32 s100, s68, 0x16156c40
	s_addc_u32 s101, s69, 0
	global_load_dwordx2 v[98:99], v20, s[100:101] sc1
	s_add_u32 s100, s68, 0x16158c40
	s_addc_u32 s101, s69, 0
	global_load_dwordx2 v[100:101], v20, s[100:101] sc1
	s_add_u32 s100, s68, 0x1615ac40
	s_addc_u32 s101, s69, 0
	global_load_dwordx2 v[102:103], v20, s[100:101] sc1
	s_add_u32 s100, s68, 0x1615cc40
	s_addc_u32 s101, s69, 0
	global_load_dwordx2 v[104:105], v20, s[100:101] sc1
	s_add_u32 s100, s68, 0x1615ec40
	s_addc_u32 s101, s69, 0
	global_load_dwordx2 v[106:107], v20, s[100:101] sc1
	s_add_u32 s100, s68, 0x16160c40
	s_addc_u32 s101, s69, 0
	global_load_dwordx2 v[108:109], v20, s[100:101] sc1
	s_add_u32 s100, s68, 0x16162c40
	s_addc_u32 s101, s69, 0
	global_load_dwordx2 v[110:111], v20, s[100:101] sc1
	s_add_u32 s100, s68, 0x16164c40
	s_addc_u32 s101, s69, 0
	global_load_dwordx2 v[112:113], v20, s[100:101] sc1
	s_add_u32 s100, s68, 0x16166c40
	s_addc_u32 s101, s69, 0
	global_load_dwordx2 v[114:115], v20, s[100:101] sc1
	s_branch .Lcf_ret1
.Lcf_scan_3:
	v_mov_b32_e32 v24, 1.0
	v_mov_b32_e32 v25, 0
	s_waitcnt vmcnt(30)
	v_fma_f32 v25, v120, v25, v121
	v_mul_f32_e32 v24, v24, v120
	s_waitcnt vmcnt(29)
	v_fma_f32 v25, v122, v25, v123
	v_mul_f32_e32 v24, v24, v122
	s_waitcnt vmcnt(28)
	v_fma_f32 v25, v124, v25, v125
	v_mul_f32_e32 v24, v24, v124
	s_waitcnt vmcnt(27)
	v_fma_f32 v25, v126, v25, v127
	v_mul_f32_e32 v24, v24, v126
	s_waitcnt vmcnt(26)
	v_fma_f32 v25, v128, v25, v129
	v_mul_f32_e32 v24, v24, v128
	s_waitcnt vmcnt(25)
	v_fma_f32 v25, v130, v25, v131
	v_mul_f32_e32 v24, v24, v130
	s_waitcnt vmcnt(24)
	v_fma_f32 v25, v132, v25, v133
	v_mul_f32_e32 v24, v24, v132
	s_waitcnt vmcnt(23)
	v_fma_f32 v25, v134, v25, v135
	v_mul_f32_e32 v24, v24, v134
	s_waitcnt vmcnt(22)
	v_fma_f32 v25, v64, v25, v65
	v_mul_f32_e32 v24, v24, v64
	s_waitcnt vmcnt(21)
	v_fma_f32 v25, v66, v25, v67
	v_mul_f32_e32 v24, v24, v66
	s_waitcnt vmcnt(20)
	v_fma_f32 v25, v68, v25, v69
	v_mul_f32_e32 v24, v24, v68
	s_waitcnt vmcnt(19)
	v_fma_f32 v25, v70, v25, v71
	v_mul_f32_e32 v24, v24, v70
	s_waitcnt vmcnt(18)
	v_fma_f32 v25, v78, v25, v79
	v_mul_f32_e32 v24, v24, v78
	s_waitcnt vmcnt(17)
	v_fma_f32 v25, v80, v25, v81
	v_mul_f32_e32 v24, v24, v80
	s_waitcnt vmcnt(16)
	v_fma_f32 v25, v82, v25, v83
	v_mul_f32_e32 v24, v24, v82
	s_waitcnt vmcnt(15)
	v_fma_f32 v25, v84, v25, v85
	v_mul_f32_e32 v24, v24, v84
	s_waitcnt vmcnt(14)
	v_fma_f32 v25, v86, v25, v87
	v_mul_f32_e32 v24, v24, v86
	s_waitcnt vmcnt(13)
	v_fma_f32 v25, v88, v25, v89
	v_mul_f32_e32 v24, v24, v88
	s_waitcnt vmcnt(12)
	v_fma_f32 v25, v90, v25, v91
	v_mul_f32_e32 v24, v24, v90
	s_waitcnt vmcnt(11)
	v_fma_f32 v25, v92, v25, v93
	v_mul_f32_e32 v24, v24, v92
	s_waitcnt vmcnt(10)
	v_fma_f32 v25, v94, v25, v95
	v_mul_f32_e32 v24, v24, v94
	s_waitcnt vmcnt(9)
	v_fma_f32 v25, v96, v25, v97
	v_mul_f32_e32 v24, v24, v96
	s_waitcnt vmcnt(8)
	v_fma_f32 v25, v98, v25, v99
	v_mul_f32_e32 v24, v24, v98
	s_waitcnt vmcnt(7)
	v_fma_f32 v25, v100, v25, v101
	v_mul_f32_e32 v24, v24, v100
	s_waitcnt vmcnt(6)
	v_fma_f32 v25, v102, v25, v103
	v_mul_f32_e32 v24, v24, v102
	s_waitcnt vmcnt(5)
	v_fma_f32 v25, v104, v25, v105
	v_mul_f32_e32 v24, v24, v104
	s_waitcnt vmcnt(4)
	v_fma_f32 v25, v106, v25, v107
	v_mul_f32_e32 v24, v24, v106
	s_waitcnt vmcnt(3)
	v_fma_f32 v25, v108, v25, v109
	v_mul_f32_e32 v24, v24, v108
	s_waitcnt vmcnt(2)
	v_fma_f32 v25, v110, v25, v111
	v_mul_f32_e32 v24, v24, v110
	s_waitcnt vmcnt(1)
	v_fma_f32 v25, v112, v25, v113
	v_mul_f32_e32 v24, v24, v112
	s_waitcnt vmcnt(0)
	v_fma_f32 v25, v114, v25, v115
	v_mul_f32_e32 v24, v24, v114
	ds_write_b64 v22, v[24:25] offset:1536
	s_waitcnt lgkmcnt(0)
	s_barrier
	v_mov_b32_e32 v26, 0
	ds_read_b64 v[28:29], v22 offset:0
	s_waitcnt lgkmcnt(0)
	v_fma_f32 v26, v28, v26, v29
	ds_read_b64 v[28:29], v22 offset:512
	s_waitcnt lgkmcnt(0)
	v_fma_f32 v26, v28, v26, v29
	ds_read_b64 v[28:29], v22 offset:1024
	s_waitcnt lgkmcnt(0)
	v_fma_f32 v26, v28, v26, v29
	s_cmp_eq_u32 s99, 3
	s_cbranch_scc0 .Lcf_skip_3_0
	s_add_u32 s100, s68, 0x162cfc40
	s_addc_u32 s101, s69, 0
	global_store_dword v21, v26, s[100:101]
.Lcf_skip_3_0:
	v_fma_f32 v26, v120, v26, v121
	s_cmp_eq_u32 s99, 4
	s_cbranch_scc0 .Lcf_skip_3_1
	s_add_u32 s100, s68, 0x162d0c40
	s_addc_u32 s101, s69, 0
	global_store_dword v21, v26, s[100:101]
.Lcf_skip_3_1:
	v_fma_f32 v26, v122, v26, v123
	s_cmp_eq_u32 s99, 5
	s_cbranch_scc0 .Lcf_skip_3_2
	s_add_u32 s100, s68, 0x162d1c40
	s_addc_u32 s101, s69, 0
	global_store_dword v21, v26, s[100:101]
.Lcf_skip_3_2:
	v_fma_f32 v26, v124, v26, v125
	s_cmp_eq_u32 s99, 6
	s_cbranch_scc0 .Lcf_skip_3_3
	s_add_u32 s100, s68, 0x162d2c40
	s_addc_u32 s101, s69, 0
	global_store_dword v21, v26, s[100:101]
.Lcf_skip_3_3:
	v_fma_f32 v26, v126, v26, v127
	s_cmp_eq_u32 s99, 7
	s_cbranch_scc0 .Lcf_skip_3_4
	s_add_u32 s100, s68, 0x162d3c40
	s_addc_u32 s101, s69, 0
	global_store_dword v21, v26, s[100:101]
.Lcf_skip_3_4:
	v_fma_f32 v26, v128, v26, v129
	s_cmp_eq_u32 s99, 8
	s_cbranch_scc0 .Lcf_skip_3_5
	s_add_u32 s100, s68, 0x162d4c40
	s_addc_u32 s101, s69, 0
	global_store_dword v21, v26, s[100:101]
.Lcf_skip_3_5:
	v_fma_f32 v26, v130, v26, v131
	s_cmp_eq_u32 s99, 9
	s_cbranch_scc0 .Lcf_skip_3_6
	s_add_u32 s100, s68, 0x162d5c40
	s_addc_u32 s101, s69, 0
	global_store_dword v21, v26, s[100:101]
.Lcf_skip_3_6:
	v_fma_f32 v26, v132, v26, v133
	s_cmp_eq_u32 s99, 10
	s_cbranch_scc0 .Lcf_skip_3_7
	s_add_u32 s100, s68, 0x162d6c40
	s_addc_u32 s101, s69, 0
	global_store_dword v21, v26, s[100:101]
.Lcf_skip_3_7:
	v_fma_f32 v26, v134, v26, v135
	s_cmp_eq_u32 s99, 11
	s_cbranch_scc0 .Lcf_skip_3_8
	s_add_u32 s100, s68, 0x162d7c40
	s_addc_u32 s101, s69, 0
	global_store_dword v21, v26, s[100:101]

.Lcf_var_4:
	s_add_u32 s100, s68, 0x1616ac40
	s_addc_u32 s101, s69, 0
	global_load_dwordx2 v[120:121], v20, s[100:101] sc1
	s_add_u32 s100, s68, 0x16168c40
	s_addc_u32 s101, s69, 0
	global_load_dwordx2 v[122:123], v20, s[100:101] sc1
	s_add_u32 s100, s68, 0x1626ac40
	s_addc_u32 s101, s69, 0
	global_load_dwordx2 v[124:125], v20, s[100:101] sc1
	s_add_u32 s100, s68, 0x16268c40
	s_addc_u32 s101, s69, 0
	global_load_dwordx2 v[126:127], v20, s[100:101] sc1
	s_add_u32 s100, s68, 0x16266c40
	s_addc_u32 s101, s69, 0
	global_load_dwordx2 v[128:129], v20, s[100:101] sc1
	s_add_u32 s100, s68, 0x16264c40
	s_addc_u32 s101, s69, 0
	global_load_dwordx2 v[130:131], v20, s[100:101] sc1
	s_add_u32 s100, s68, 0x16262c40
	s_addc_u32 s101, s69, 0
	global_load_dwordx2 v[132:133], v20, s[100:101] sc1
	s_add_u32 s100, s68, 0x16260c40
	s_addc_u32 s101, s69, 0
	global_load_dwordx2 v[134:135], v20, s[100:101] sc1
	s_add_u32 s100, s68, 0x1625ec40
	s_addc_u32 s101, s69, 0
	global_load_dwordx2 v[64:65], v20, s[100:101] sc1
	s_add_u32 s100, s68, 0x1625cc40
	s_addc_u32 s101, s69, 0
	global_load_dwordx2 v[66:67], v20, s[100:101] sc1
	s_add_u32 s100, s68, 0x1625ac40
	s_addc_u32 s101, s69, 0
	global_load_dwordx2 v[68:69], v20, s[100:101] sc1
	s_add_u32 s100, s68, 0x16258c40
	s_addc_u32 s101, s69, 0
	global_load_dwordx2 v[70:71], v20, s[100:101] sc1
	s_add_u32 s100, s68, 0x16256c40
	s_addc_u32 s101, s69, 0
	global_load_dwordx2 v[78:79], v20, s[100:101] sc1
	s_add_u32 s100, s68, 0x16254c40
	s_addc_u32 s101, s69, 0
	global_load_dwordx2 v[80:81], v20, s[100:101] sc1
	s_add_u32 s100, s68, 0x16252c40
	s_addc_u32 s101, s69, 0
	global_load_dwordx2 v[82:83], v20, s[100:101] sc1
	s_add_u32 s100, s68, 0x16250c40
	s_addc_u32 s101, s69, 0
	global_load_dwordx2 v[84:85], v20, s[100:101] sc1
	s_add_u32 s100, s68, 0x1624ec40
	s_addc_u32 s101, s69, 0
	global_load_dwordx2 v[86:87], v20, s[100:101] sc1
	s_add_u32 s100, s68, 0x1624cc40
	s_addc_u32 s101, s69, 0
	global_load_dwordx2 v[88:89], v20, s[100:101] sc1
	s_add_u32 s100, s68, 0x1624ac40
	s_addc_u32 s101, s69, 0
	global_load_dwordx2 v[90:91], v20, s[100:101] sc1
	s_add_u32 s100, s68, 0x16248c40
	s_addc_u32 s101, s69, 0
	global_load_dwordx2 v[92:93], v20, s[100:101] sc1
	s_add_u32 s100, s68, 0x16246c40
	s_addc_u32 s101, s69, 0
	global_load_dwordx2 v[94:95], v20, s[100:101] sc1
	s_add_u32 s100, s68, 0x16244c40
	s_addc_u32 s101, s69, 0
	global_load_dwordx2 v[96:97], v20, s[100:101] sc1
	s_add_u32 s100, s68, 0x16242c40
	s_addc_u32 s101, s69, 0
	global_load_dwordx2 v[98:99], v20, s[100:101] sc1
	s_add_u32 s100, s68, 0x16240c40
	s_addc_u32 s101, s69, 0
	global_load_dwordx2 v[100:101], v20, s[100:101] sc1
	s_add_u32 s100, s68, 0x1623ec40
	s_addc_u32 s101, s69, 0
	global_load_dwordx2 v[102:103], v20, s[100:101] sc1
	s_add_u32 s100, s68, 0x1623cc40
	s_addc_u32 s101, s69, 0
	global_load_dwordx2 v[104:105], v20, s[100:101] sc1
	s_add_u32 s100, s68, 0x1623ac40
	s_addc_u32 s101, s69, 0
	global_load_dwordx2 v[106:107], v20, s[100:101] sc1
	s_add_u32 s100, s68, 0x16238c40
	s_addc_u32 s101, s69, 0
	global_load_dwordx2 v[108:109], v20, s[100:101] sc1
	s_add_u32 s100, s68, 0x16236c40
	s_addc_u32 s101, s69, 0
	global_load_dwordx2 v[110:111], v20, s[100:101] sc1
	s_add_u32 s100, s68, 0x16234c40
	s_addc_u32 s101, s69, 0
	global_load_dwordx2 v[112:113], v20, s[100:101] sc1
	s_add_u32 s100, s68, 0x16232c40
	s_addc_u32 s101, s69, 0
	global_load_dwordx2 v[114:115], v20, s[100:101] sc1
	s_add_u32 s100, s68, 0x16230c40
	s_addc_u32 s101, s69, 0
	global_load_dwordx2 v[116:117], v20, s[100:101] sc1
	s_add_u32 s100, s68, 0x1622ec40
	s_addc_u32 s101, s69, 0
	global_load_dwordx2 v[118:119], v20, s[100:101] sc1
	s_branch .Lcf_ret1
.Lcf_scan_4:
	v_mov_b32_e32 v24, 1.0
	v_mov_b32_e32 v25, 0
	s_waitcnt vmcnt(32)
	v_fma_f32 v25, v120, v25, v121
	v_mul_f32_e32 v24, v24, v120
	s_waitcnt vmcnt(31)
	v_fma_f32 v25, v122, v25, v123
	v_mul_f32_e32 v24, v24, v122
	s_waitcnt vmcnt(30)
	v_fma_f32 v25, v124, v25, v125
	v_mul_f32_e32 v24, v24, v124
	s_waitcnt vmcnt(29)
	v_fma_f32 v25, v126, v25, v127
	v_mul_f32_e32 v24, v24, v126
	s_waitcnt vmcnt(28)
	v_fma_f32 v25, v128, v25, v129
	v_mul_f32_e32 v24, v24, v128
	s_waitcnt vmcnt(27)
	v_fma_f32 v25, v130, v25, v131
	v_mul_f32_e32 v24, v24, v130
	s_waitcnt vmcnt(26)
	v_fma_f32 v25, v132, v25, v133
	v_mul_f32_e32 v24, v24, v132
	s_waitcnt vmcnt(25)
	v_fma_f32 v25, v134, v25, v135
	v_mul_f32_e32 v24, v24, v134
	s_waitcnt vmcnt(24)
	v_fma_f32 v25, v64, v25, v65
	v_mul_f32_e32 v24, v24, v64
	s_waitcnt vmcnt(23)
	v_fma_f32 v25, v66, v25, v67
	v_mul_f32_e32 v24, v24, v66
	s_waitcnt vmcnt(22)
	v_fma_f32 v25, v68, v25, v69
	v_mul_f32_e32 v24, v24, v68
	s_waitcnt vmcnt(21)
	v_fma_f32 v25, v70, v25, v71
	v_mul_f32_e32 v24, v24, v70
	s_waitcnt vmcnt(20)
	v_fma_f32 v25, v78, v25, v79
	v_mul_f32_e32 v24, v24, v78
	s_waitcnt vmcnt(19)
	v_fma_f32 v25, v80, v25, v81
	v_mul_f32_e32 v24, v24, v80
	s_waitcnt vmcnt(18)
	v_fma_f32 v25, v82, v25, v83
	v_mul_f32_e32 v24, v24, v82
	s_waitcnt vmcnt(17)
	v_fma_f32 v25, v84, v25, v85
	v_mul_f32_e32 v24, v24, v84
	s_waitcnt vmcnt(16)
	v_fma_f32 v25, v86, v25, v87
	v_mul_f32_e32 v24, v24, v86
	s_waitcnt vmcnt(15)
	v_fma_f32 v25, v88, v25, v89
	v_mul_f32_e32 v24, v24, v88
	s_waitcnt vmcnt(14)
	v_fma_f32 v25, v90, v25, v91
	v_mul_f32_e32 v24, v24, v90
	s_waitcnt vmcnt(13)
	v_fma_f32 v25, v92, v25, v93
	v_mul_f32_e32 v24, v24, v92
	s_waitcnt vmcnt(12)
	v_fma_f32 v25, v94, v25, v95
	v_mul_f32_e32 v24, v24, v94
	s_waitcnt vmcnt(11)
	v_fma_f32 v25, v96, v25, v97
	v_mul_f32_e32 v24, v24, v96
	s_waitcnt vmcnt(10)
	v_fma_f32 v25, v98, v25, v99
	v_mul_f32_e32 v24, v24, v98
	s_waitcnt vmcnt(9)
	v_fma_f32 v25, v100, v25, v101
	v_mul_f32_e32 v24, v24, v100
	s_waitcnt vmcnt(8)
	v_fma_f32 v25, v102, v25, v103
	v_mul_f32_e32 v24, v24, v102
	s_waitcnt vmcnt(7)
	v_fma_f32 v25, v104, v25, v105
	v_mul_f32_e32 v24, v24, v104
	s_waitcnt vmcnt(6)
	v_fma_f32 v25, v106, v25, v107
	v_mul_f32_e32 v24, v24, v106
	s_waitcnt vmcnt(5)
	v_fma_f32 v25, v108, v25, v109
	v_mul_f32_e32 v24, v24, v108
	s_waitcnt vmcnt(4)
	v_fma_f32 v25, v110, v25, v111
	v_mul_f32_e32 v24, v24, v110
	s_waitcnt vmcnt(3)
	v_fma_f32 v25, v112, v25, v113
	v_mul_f32_e32 v24, v24, v112
	s_waitcnt vmcnt(2)
	v_fma_f32 v25, v114, v25, v115
	v_mul_f32_e32 v24, v24, v114
	s_waitcnt vmcnt(1)
	v_fma_f32 v25, v116, v25, v117
	v_mul_f32_e32 v24, v24, v116
	s_waitcnt vmcnt(0)
	v_fma_f32 v25, v118, v25, v119
	v_mul_f32_e32 v24, v24, v118
	ds_write_b64 v22, v[24:25] offset:2048
	s_waitcnt lgkmcnt(0)
	s_barrier
	v_mov_b32_e32 v26, 0
	s_cmp_eq_u32 s99, 1
	s_cbranch_scc0 .Lcf_skip_4_0
	s_add_u32 s100, s68, 0x162efc40
	s_addc_u32 s101, s69, 0
	global_store_dword v21, v26, s[100:101]
.Lcf_skip_4_0:
	v_fma_f32 v26, v120, v26, v121
	s_cmp_eq_u32 s99, 0
	s_cbranch_scc0 .Lcf_skip_4_1
	s_add_u32 s100, s68, 0x162eec40
	s_addc_u32 s101, s69, 0
	global_store_dword v21, v26, s[100:101]
.Lcf_skip_4_1:
	v_fma_f32 v26, v122, v26, v123
	s_cmp_eq_u32 s99, 1
	s_cbranch_scc0 .Lcf_skip_4_2
	s_add_u32 s100, s68, 0x1636fc40
	s_addc_u32 s101, s69, 0
	global_store_dword v21, v26, s[100:101]
.Lcf_skip_4_2:
	v_fma_f32 v26, v124, v26, v125
	s_cmp_eq_u32 s99, 0
	s_cbranch_scc0 .Lcf_skip_4_3
	s_add_u32 s100, s68, 0x1636ec40
	s_addc_u32 s101, s69, 0
	global_store_dword v21, v26, s[100:101]
.Lcf_skip_4_3:
	v_fma_f32 v26, v126, v26, v127
	s_cmp_eq_u32 s99, 15
	s_cbranch_scc0 .Lcf_skip_4_4
	s_add_u32 s100, s68, 0x1636dc40
	s_addc_u32 s101, s69, 0
	global_store_dword v21, v26, s[100:101]
.Lcf_skip_4_4:
	v_fma_f32 v26, v128, v26, v129
	s_cmp_eq_u32 s99, 14
	s_cbranch_scc0 .Lcf_skip_4_5
	s_add_u32 s100, s68, 0x1636cc40
	s_addc_u32 s101, s69, 0
	global_store_dword v21, v26, s[100:101]
.Lcf_skip_4_5:
	v_fma_f32 v26, v130, v26, v131
	s_cmp_eq_u32 s99, 13
	s_cbranch_scc0 .Lcf_skip_4_6
	s_add_u32 s100, s68, 0x1636bc40
	s_addc_u32 s101, s69, 0
	global_store_dword v21, v26, s[100:101]
.Lcf_skip_4_6:
	v_fma_f32 v26, v132, v26, v133
	s_cmp_eq_u32 s99, 12
	s_cbranch_scc0 .Lcf_skip_4_7
	s_add_u32 s100, s68, 0x1636ac40
	s_addc_u32 s101, s69, 0
	global_store_dword v21, v26, s[100:101]
.Lcf_skip_4_7:
	v_fma_f32 v26, v134, v26, v135
	s_cmp_eq_u32 s99, 11
	s_cbranch_scc0 .Lcf_skip_4_8
	s_add_u32 s100, s68, 0x16369c40
	s_addc_u32 s101, s69, 0
	global_store_dword v21, v26, s[100:101]

.Lcf_var_5:
	s_add_u32 s100, s68, 0x1622cc40
	s_addc_u32 s101, s69, 0
	global_load_dwordx2 v[120:121], v20, s[100:101] sc1
	s_add_u32 s100, s68, 0x1622ac40
	s_addc_u32 s101, s69, 0
	global_load_dwordx2 v[122:123], v20, s[100:101] sc1
	s_add_u32 s100, s68, 0x16228c40
	s_addc_u32 s101, s69, 0
	global_load_dwordx2 v[124:125], v20, s[100:101] sc1
	s_add_u32 s100, s68, 0x16226c40
	s_addc_u32 s101, s69, 0
	global_load_dwordx2 v[126:127], v20, s[100:101] sc1
	s_add_u32 s100, s68, 0x16224c40
	s_addc_u32 s101, s69, 0
	global_load_dwordx2 v[128:129], v20, s[100:101] sc1
	s_add_u32 s100, s68, 0x16222c40
	s_addc_u32 s101, s69, 0
	global_load_dwordx2 v[130:131], v20, s[100:101] sc1
	s_add_u32 s100, s68, 0x16220c40
	s_addc_u32 s101, s69, 0
	global_load_dwordx2 v[132:133], v20, s[100:101] sc1
	s_add_u32 s100, s68, 0x1621ec40
	s_addc_u32 s101, s69, 0
	global_load_dwordx2 v[134:135], v20, s[100:101] sc1
	s_add_u32 s100, s68, 0x1621cc40
	s_addc_u32 s101, s69, 0
	global_load_dwordx2 v[64:65], v20, s[100:101] sc1
	s_add_u32 s100, s68, 0x1621ac40
	s_addc_u32 s101, s69, 0
	global_load_dwordx2 v[66:67], v20, s[100:101] sc1
	s_add_u32 s100, s68, 0x16218c40
	s_addc_u32 s101, s69, 0
	global_load_dwordx2 v[68:69], v20, s[100:101] sc1
	s_add_u32 s100, s68, 0x16216c40
	s_addc_u32 s101, s69, 0
	global_load_dwordx2 v[70:71], v20, s[100:101] sc1
	s_add_u32 s100, s68, 0x16214c40
	s_addc_u32 s101, s69, 0
	global_load_dwordx2 v[78:79], v20, s[100:101] sc1
	s_add_u32 s100, s68, 0x16212c40
	s_addc_u32 s101, s69, 0
	global_load_dwordx2 v[80:81], v20, s[100:101] sc1
	s_add_u32 s100, s68, 0x16210c40
	s_addc_u32 s101, s69, 0
	global_load_dwordx2 v[82:83], v20, s[100:101] sc1
	s_add_u32 s100, s68, 0x1620ec40
	s_addc_u32 s101, s69, 0
	global_load_dwordx2 v[84:85], v20, s[100:101] sc1
	s_add_u32 s100, s68, 0x1620cc40
	s_addc_u32 s101, s69, 0
	global_load_dwordx2 v[86:87], v20, s[100:101] sc1
	s_add_u32 s100, s68, 0x1620ac40
	s_addc_u32 s101, s69, 0
	global_load_dwordx2 v[88:89], v20, s[100:101] sc1
	s_add_u32 s100, s68, 0x16208c40
	s_addc_u32 s101, s69, 0
	global_load_dwordx2 v[90:91], v20, s[100:101] sc1
	s_add_u32 s100, s68, 0x16206c40
	s_addc_u32 s101, s69, 0
	global_load_dwordx2 v[92:93], v20, s[100:101] sc1
	s_add_u32 s100, s68, 0x16204c40
	s_addc_u32 s101, s69, 0
	global_load_dwordx2 v[94:95], v20, s[100:101] sc1
	s_add_u32 s100, s68, 0x16202c40
	s_addc_u32 s101, s69, 0
	global_load_dwordx2 v[96:97], v20, s[100:101] sc1
	s_add_u32 s100, s68, 0x16200c40
	s_addc_u32 s101, s69, 0
	global_load_dwordx2 v[98:99], v20, s[100:101] sc1
	s_add_u32 s100, s68, 0x161fec40
	s_addc_u32 s101, s69, 0
	global_load_dwordx2 v[100:101], v20, s[100:101] sc1
	s_add_u32 s100, s68, 0x161fcc40
	s_addc_u32 s101, s69, 0
	global_load_dwordx2 v[102:103], v20, s[100:101] sc1
	s_add_u32 s100, s68, 0x161fac40
	s_addc_u32 s101, s69, 0
	global_load_dwordx2 v[104:105], v20, s[100:101] sc1
	s_add_u32 s100, s68, 0x161f8c40
	s_addc_u32 s101, s69, 0
	global_load_dwordx2 v[106:107], v20, s[100:101] sc1
	s_add_u32 s100, s68, 0x161f6c40
	s_addc_u32 s101, s69, 0
	global_load_dwordx2 v[108:109], v20, s[100:101] sc1
	s_add_u32 s100, s68, 0x161f4c40
	s_addc_u32 s101, s69, 0
	global_load_dwordx2 v[110:111], v20, s[100:101] sc1
	s_add_u32 s100, s68, 0x161f2c40
	s_addc_u32 s101, s69, 0
	global_load_dwordx2 v[112:113], v20, s[100:101] sc1
	s_add_u32 s100, s68, 0x161f0c40
	s_addc_u32 s101, s69, 0
	global_load_dwordx2 v[114:115], v20, s[100:101] sc1
	s_add_u32 s100, s68, 0x161eec40
	s_addc_u32 s101, s69, 0
	global_load_dwordx2 v[116:117], v20, s[100:101] sc1
	s_add_u32 s100, s68, 0x161ecc40
	s_addc_u32 s101, s69, 0
	global_load_dwordx2 v[118:119], v20, s[100:101] sc1
	s_branch .Lcf_ret1
.Lcf_scan_5:
	v_mov_b32_e32 v24, 1.0
	v_mov_b32_e32 v25, 0
	s_waitcnt vmcnt(32)
	v_fma_f32 v25, v120, v25, v121
	v_mul_f32_e32 v24, v24, v120
	s_waitcnt vmcnt(31)
	v_fma_f32 v25, v122, v25, v123
	v_mul_f32_e32 v24, v24, v122
	s_waitcnt vmcnt(30)
	v_fma_f32 v25, v124, v25, v125
	v_mul_f32_e32 v24, v24, v124
	s_waitcnt vmcnt(29)
	v_fma_f32 v25, v126, v25, v127
	v_mul_f32_e32 v24, v24, v126
	s_waitcnt vmcnt(28)
	v_fma_f32 v25, v128, v25, v129
	v_mul_f32_e32 v24, v24, v128
	s_waitcnt vmcnt(27)
	v_fma_f32 v25, v130, v25, v131
	v_mul_f32_e32 v24, v24, v130
	s_waitcnt vmcnt(26)
	v_fma_f32 v25, v132, v25, v133
	v_mul_f32_e32 v24, v24, v132
	s_waitcnt vmcnt(25)
	v_fma_f32 v25, v134, v25, v135
	v_mul_f32_e32 v24, v24, v134
	s_waitcnt vmcnt(24)
	v_fma_f32 v25, v64, v25, v65
	v_mul_f32_e32 v24, v24, v64
	s_waitcnt vmcnt(23)
	v_fma_f32 v25, v66, v25, v67
	v_mul_f32_e32 v24, v24, v66
	s_waitcnt vmcnt(22)
	v_fma_f32 v25, v68, v25, v69
	v_mul_f32_e32 v24, v24, v68
	s_waitcnt vmcnt(21)
	v_fma_f32 v25, v70, v25, v71
	v_mul_f32_e32 v24, v24, v70
	s_waitcnt vmcnt(20)
	v_fma_f32 v25, v78, v25, v79
	v_mul_f32_e32 v24, v24, v78
	s_waitcnt vmcnt(19)
	v_fma_f32 v25, v80, v25, v81
	v_mul_f32_e32 v24, v24, v80
	s_waitcnt vmcnt(18)
	v_fma_f32 v25, v82, v25, v83
	v_mul_f32_e32 v24, v24, v82
	s_waitcnt vmcnt(17)
	v_fma_f32 v25, v84, v25, v85
	v_mul_f32_e32 v24, v24, v84
	s_waitcnt vmcnt(16)
	v_fma_f32 v25, v86, v25, v87
	v_mul_f32_e32 v24, v24, v86
	s_waitcnt vmcnt(15)
	v_fma_f32 v25, v88, v25, v89
	v_mul_f32_e32 v24, v24, v88
	s_waitcnt vmcnt(14)
	v_fma_f32 v25, v90, v25, v91
	v_mul_f32_e32 v24, v24, v90
	s_waitcnt vmcnt(13)
	v_fma_f32 v25, v92, v25, v93
	v_mul_f32_e32 v24, v24, v92
	s_waitcnt vmcnt(12)
	v_fma_f32 v25, v94, v25, v95
	v_mul_f32_e32 v24, v24, v94
	s_waitcnt vmcnt(11)
	v_fma_f32 v25, v96, v25, v97
	v_mul_f32_e32 v24, v24, v96
	s_waitcnt vmcnt(10)
	v_fma_f32 v25, v98, v25, v99
	v_mul_f32_e32 v24, v24, v98
	s_waitcnt vmcnt(9)
	v_fma_f32 v25, v100, v25, v101
	v_mul_f32_e32 v24, v24, v100
	s_waitcnt vmcnt(8)
	v_fma_f32 v25, v102, v25, v103
	v_mul_f32_e32 v24, v24, v102
	s_waitcnt vmcnt(7)
	v_fma_f32 v25, v104, v25, v105
	v_mul_f32_e32 v24, v24, v104
	s_waitcnt vmcnt(6)
	v_fma_f32 v25, v106, v25, v107
	v_mul_f32_e32 v24, v24, v106
	s_waitcnt vmcnt(5)
	v_fma_f32 v25, v108, v25, v109
	v_mul_f32_e32 v24, v24, v108
	s_waitcnt vmcnt(4)
	v_fma_f32 v25, v110, v25, v111
	v_mul_f32_e32 v24, v24, v110
	s_waitcnt vmcnt(3)
	v_fma_f32 v25, v112, v25, v113
	v_mul_f32_e32 v24, v24, v112
	s_waitcnt vmcnt(2)
	v_fma_f32 v25, v114, v25, v115
	v_mul_f32_e32 v24, v24, v114
	s_waitcnt vmcnt(1)
	v_fma_f32 v25, v116, v25, v117
	v_mul_f32_e32 v24, v24, v116
	s_waitcnt vmcnt(0)
	v_fma_f32 v25, v118, v25, v119
	v_mul_f32_e32 v24, v24, v118
	ds_write_b64 v22, v[24:25] offset:2560
	s_waitcnt lgkmcnt(0)
	s_barrier
	v_mov_b32_e32 v26, 0
	ds_read_b64 v[28:29], v22 offset:2048
	s_waitcnt lgkmcnt(0)
	v_fma_f32 v26, v28, v26, v29
	s_cmp_eq_u32 s99, 2
	s_cbranch_scc0 .Lcf_skip_5_0
	s_add_u32 s100, s68, 0x16350c40
	s_addc_u32 s101, s69, 0
	global_store_dword v21, v26, s[100:101]
.Lcf_skip_5_0:
	v_fma_f32 v26, v120, v26, v121
	s_cmp_eq_u32 s99, 1
	s_cbranch_scc0 .Lcf_skip_5_1
	s_add_u32 s100, s68, 0x1634fc40
	s_addc_u32 s101, s69, 0
	global_store_dword v21, v26, s[100:101]
.Lcf_skip_5_1:
	v_fma_f32 v26, v122, v26, v123
	s_cmp_eq_u32 s99, 0
	s_cbranch_scc0 .Lcf_skip_5_2
	s_add_u32 s100, s68, 0x1634ec40
	s_addc_u32 s101, s69, 0
	global_store_dword v21, v26, s[100:101]
.Lcf_skip_5_2:
	v_fma_f32 v26, v124, v26, v125
	s_cmp_eq_u32 s99, 15
	s_cbranch_scc0 .Lcf_skip_5_3
	s_add_u32 s100, s68, 0x1634dc40
	s_addc_u32 s101, s69, 0
	global_store_dword v21, v26, s[100:101]
.Lcf_skip_5_3:
	v_fma_f32 v26, v126, v26, v127
	s_cmp_eq_u32 s99, 14
	s_cbranch_scc0 .Lcf_skip_5_4
	s_add_u32 s100, s68, 0x1634cc40
	s_addc_u32 s101, s69, 0
	global_store_dword v21, v26, s[100:101]
.Lcf_skip_5_4:
	v_fma_f32 v26, v128, v26, v129
	s_cmp_eq_u32 s99, 13
	s_cbranch_scc0 .Lcf_skip_5_5
	s_add_u32 s100, s68, 0x1634bc40
	s_addc_u32 s101, s69, 0
	global_store_dword v21, v26, s[100:101]
.Lcf_skip_5_5:
	v_fma_f32 v26, v130, v26, v131
	s_cmp_eq_u32 s99, 12
	s_cbranch_scc0 .Lcf_skip_5_6
	s_add_u32 s100, s68, 0x1634ac40
	s_addc_u32 s101, s69, 0
	global_store_dword v21, v26, s[100:101]
.Lcf_skip_5_6:
	v_fma_f32 v26, v132, v26, v133
	s_cmp_eq_u32 s99, 11
	s_cbranch_scc0 .Lcf_skip_5_7
	s_add_u32 s100, s68, 0x16349c40
	s_addc_u32 s101, s69, 0
	global_store_dword v21, v26, s[100:101]
.Lcf_skip_5_7:
	v_fma_f32 v26, v134, v26, v135
	s_cmp_eq_u32 s99, 10
	s_cbranch_scc0 .Lcf_skip_5_8
	s_add_u32 s100, s68, 0x16348c40
	s_addc_u32 s101, s69, 0
	global_store_dword v21, v26, s[100:101]

.Lcf_var_6:
	s_add_u32 s100, s68, 0x161eac40
	s_addc_u32 s101, s69, 0
	global_load_dwordx2 v[120:121], v20, s[100:101] sc1
	s_add_u32 s100, s68, 0x161e8c40
	s_addc_u32 s101, s69, 0
	global_load_dwordx2 v[122:123], v20, s[100:101] sc1
	s_add_u32 s100, s68, 0x161e6c40
	s_addc_u32 s101, s69, 0
	global_load_dwordx2 v[124:125], v20, s[100:101] sc1
	s_add_u32 s100, s68, 0x161e4c40
	s_addc_u32 s101, s69, 0
	global_load_dwordx2 v[126:127], v20, s[100:101] sc1
	s_add_u32 s100, s68, 0x161e2c40
	s_addc_u32 s101, s69, 0
	global_load_dwordx2 v[128:129], v20, s[100:101] sc1
	s_add_u32 s100, s68, 0x161e0c40
	s_addc_u32 s101, s69, 0
	global_load_dwordx2 v[130:131], v20, s[100:101] sc1
	s_add_u32 s100, s68, 0x161dec40
	s_addc_u32 s101, s69, 0
	global_load_dwordx2 v[132:133], v20, s[100:101] sc1
	s_add_u32 s100, s68, 0x161dcc40
	s_addc_u32 s101, s69, 0
	global_load_dwordx2 v[134:135], v20, s[100:101] sc1
	s_add_u32 s100, s68, 0x161dac40
	s_addc_u32 s101, s69, 0
	global_load_dwordx2 v[64:65], v20, s[100:101] sc1
	s_add_u32 s100, s68, 0x161d8c40
	s_addc_u32 s101, s69, 0
	global_load_dwordx2 v[66:67], v20, s[100:101] sc1
	s_add_u32 s100, s68, 0x161d6c40
	s_addc_u32 s101, s69, 0
	global_load_dwordx2 v[68:69], v20, s[100:101] sc1
	s_add_u32 s100, s68, 0x161d4c40
	s_addc_u32 s101, s69, 0
	global_load_dwordx2 v[70:71], v20, s[100:101] sc1
	s_add_u32 s100, s68, 0x161d2c40
	s_addc_u32 s101, s69, 0
	global_load_dwordx2 v[78:79], v20, s[100:101] sc1
	s_add_u32 s100, s68, 0x161d0c40
	s_addc_u32 s101, s69, 0
	global_load_dwordx2 v[80:81], v20, s[100:101] sc1
	s_add_u32 s100, s68, 0x161cec40
	s_addc_u32 s101, s69, 0
	global_load_dwordx2 v[82:83], v20, s[100:101] sc1
	s_add_u32 s100, s68, 0x161ccc40
	s_addc_u32 s101, s69, 0
	global_load_dwordx2 v[84:85], v20, s[100:101] sc1
	s_add_u32 s100, s68, 0x161cac40
	s_addc_u32 s101, s69, 0
	global_load_dwordx2 v[86:87], v20, s[100:101] sc1
	s_add_u32 s100, s68, 0x161c8c40
	s_addc_u32 s101, s69, 0
	global_load_dwordx2 v[88:89], v20, s[100:101] sc1
	s_add_u32 s100, s68, 0x161c6c40
	s_addc_u32 s101, s69, 0
	global_load_dwordx2 v[90:91], v20, s[100:101] sc1
	s_add_u32 s100, s68, 0x161c4c40
	s_addc_u32 s101, s69, 0
	global_load_dwordx2 v[92:93], v20, s[100:101] sc1
	s_add_u32 s100, s68, 0x161c2c40
	s_addc_u32 s101, s69, 0
	global_load_dwordx2 v[94:95], v20, s[100:101] sc1
	s_add_u32 s100, s68, 0x161c0c40
	s_addc_u32 s101, s69, 0
	global_load_dwordx2 v[96:97], v20, s[100:101] sc1
	s_add_u32 s100, s68, 0x161bec40
	s_addc_u32 s101, s69, 0
	global_load_dwordx2 v[98:99], v20, s[100:101] sc1
	s_add_u32 s100, s68, 0x161bcc40
	s_addc_u32 s101, s69, 0
	global_load_dwordx2 v[100:101], v20, s[100:101] sc1
	s_add_u32 s100, s68, 0x161bac40
	s_addc_u32 s101, s69, 0
	global_load_dwordx2 v[102:103], v20, s[100:101] sc1
	s_add_u32 s100, s68, 0x161b8c40
	s_addc_u32 s101, s69, 0
	global_load_dwordx2 v[104:105], v20, s[100:101] sc1
	s_add_u32 s100, s68, 0x161b6c40
	s_addc_u32 s101, s69, 0
	global_load_dwordx2 v[106:107], v20, s[100:101] sc1
	s_add_u32 s100, s68, 0x161b4c40
	s_addc_u32 s101, s69, 0
	global_load_dwordx2 v[108:109], v20, s[100:101] sc1
	s_add_u32 s100, s68, 0x161b2c40
	s_addc_u32 s101, s69, 0
	global_load_dwordx2 v[110:111], v20, s[100:101] sc1
	s_add_u32 s100, s68, 0x161b0c40
	s_addc_u32 s101, s69, 0
	global_load_dwordx2 v[112:113], v20, s[100:101] sc1
	s_add_u32 s100, s68, 0x161aec40
	s_addc_u32 s101, s69, 0
	global_load_dwordx2 v[114:115], v20, s[100:101] sc1
	s_add_u32 s100, s68, 0x161acc40
	s_addc_u32 s101, s69, 0
	global_load_dwordx2 v[116:117], v20, s[100:101] sc1
	s_add_u32 s100, s68, 0x161aac40
	s_addc_u32 s101, s69, 0
	global_load_dwordx2 v[118:119], v20, s[100:101] sc1
	s_branch .Lcf_ret1
.Lcf_scan_6:
	v_mov_b32_e32 v24, 1.0
	v_mov_b32_e32 v25, 0
	s_waitcnt vmcnt(32)
	v_fma_f32 v25, v120, v25, v121
	v_mul_f32_e32 v24, v24, v120
	s_waitcnt vmcnt(31)
	v_fma_f32 v25, v122, v25, v123
	v_mul_f32_e32 v24, v24, v122
	s_waitcnt vmcnt(30)
	v_fma_f32 v25, v124, v25, v125
	v_mul_f32_e32 v24, v24, v124
	s_waitcnt vmcnt(29)
	v_fma_f32 v25, v126, v25, v127
	v_mul_f32_e32 v24, v24, v126
	s_waitcnt vmcnt(28)
	v_fma_f32 v25, v128, v25, v129
	v_mul_f32_e32 v24, v24, v128
	s_waitcnt vmcnt(27)
	v_fma_f32 v25, v130, v25, v131
	v_mul_f32_e32 v24, v24, v130
	s_waitcnt vmcnt(26)
	v_fma_f32 v25, v132, v25, v133
	v_mul_f32_e32 v24, v24, v132
	s_waitcnt vmcnt(25)
	v_fma_f32 v25, v134, v25, v135
	v_mul_f32_e32 v24, v24, v134
	s_waitcnt vmcnt(24)
	v_fma_f32 v25, v64, v25, v65
	v_mul_f32_e32 v24, v24, v64
	s_waitcnt vmcnt(23)
	v_fma_f32 v25, v66, v25, v67
	v_mul_f32_e32 v24, v24, v66
	s_waitcnt vmcnt(22)
	v_fma_f32 v25, v68, v25, v69
	v_mul_f32_e32 v24, v24, v68
	s_waitcnt vmcnt(21)
	v_fma_f32 v25, v70, v25, v71
	v_mul_f32_e32 v24, v24, v70
	s_waitcnt vmcnt(20)
	v_fma_f32 v25, v78, v25, v79
	v_mul_f32_e32 v24, v24, v78
	s_waitcnt vmcnt(19)
	v_fma_f32 v25, v80, v25, v81
	v_mul_f32_e32 v24, v24, v80
	s_waitcnt vmcnt(18)
	v_fma_f32 v25, v82, v25, v83
	v_mul_f32_e32 v24, v24, v82
	s_waitcnt vmcnt(17)
	v_fma_f32 v25, v84, v25, v85
	v_mul_f32_e32 v24, v24, v84
	s_waitcnt vmcnt(16)
	v_fma_f32 v25, v86, v25, v87
	v_mul_f32_e32 v24, v24, v86
	s_waitcnt vmcnt(15)
	v_fma_f32 v25, v88, v25, v89
	v_mul_f32_e32 v24, v24, v88
	s_waitcnt vmcnt(14)
	v_fma_f32 v25, v90, v25, v91
	v_mul_f32_e32 v24, v24, v90
	s_waitcnt vmcnt(13)
	v_fma_f32 v25, v92, v25, v93
	v_mul_f32_e32 v24, v24, v92
	s_waitcnt vmcnt(12)
	v_fma_f32 v25, v94, v25, v95
	v_mul_f32_e32 v24, v24, v94
	s_waitcnt vmcnt(11)
	v_fma_f32 v25, v96, v25, v97
	v_mul_f32_e32 v24, v24, v96
	s_waitcnt vmcnt(10)
	v_fma_f32 v25, v98, v25, v99
	v_mul_f32_e32 v24, v24, v98
	s_waitcnt vmcnt(9)
	v_fma_f32 v25, v100, v25, v101
	v_mul_f32_e32 v24, v24, v100
	s_waitcnt vmcnt(8)
	v_fma_f32 v25, v102, v25, v103
	v_mul_f32_e32 v24, v24, v102
	s_waitcnt vmcnt(7)
	v_fma_f32 v25, v104, v25, v105
	v_mul_f32_e32 v24, v24, v104
	s_waitcnt vmcnt(6)
	v_fma_f32 v25, v106, v25, v107
	v_mul_f32_e32 v24, v24, v106
	s_waitcnt vmcnt(5)
	v_fma_f32 v25, v108, v25, v109
	v_mul_f32_e32 v24, v24, v108
	s_waitcnt vmcnt(4)
	v_fma_f32 v25, v110, v25, v111
	v_mul_f32_e32 v24, v24, v110
	s_waitcnt vmcnt(3)
	v_fma_f32 v25, v112, v25, v113
	v_mul_f32_e32 v24, v24, v112
	s_waitcnt vmcnt(2)
	v_fma_f32 v25, v114, v25, v115
	v_mul_f32_e32 v24, v24, v114
	s_waitcnt vmcnt(1)
	v_fma_f32 v25, v116, v25, v117
	v_mul_f32_e32 v24, v24, v116
	s_waitcnt vmcnt(0)
	v_fma_f32 v25, v118, v25, v119
	v_mul_f32_e32 v24, v24, v118
	ds_write_b64 v22, v[24:25] offset:3072
	s_waitcnt lgkmcnt(0)
	s_barrier
	v_mov_b32_e32 v26, 0
	ds_read_b64 v[28:29], v22 offset:2048
	s_waitcnt lgkmcnt(0)
	v_fma_f32 v26, v28, v26, v29
	ds_read_b64 v[28:29], v22 offset:2560
	s_waitcnt lgkmcnt(0)
	v_fma_f32 v26, v28, v26, v29
	s_cmp_eq_u32 s99, 1
	s_cbranch_scc0 .Lcf_skip_6_0
	s_add_u32 s100, s68, 0x1632fc40
	s_addc_u32 s101, s69, 0
	global_store_dword v21, v26, s[100:101]
.Lcf_skip_6_0:
	v_fma_f32 v26, v120, v26, v121
	s_cmp_eq_u32 s99, 0
	s_cbranch_scc0 .Lcf_skip_6_1
	s_add_u32 s100, s68, 0x1632ec40
	s_addc_u32 s101, s69, 0
	global_store_dword v21, v26, s[100:101]
.Lcf_skip_6_1:
	v_fma_f32 v26, v122, v26, v123
	s_cmp_eq_u32 s99, 15
	s_cbranch_scc0 .Lcf_skip_6_2
	s_add_u32 s100, s68, 0x1632dc40
	s_addc_u32 s101, s69, 0
	global_store_dword v21, v26, s[100:101]
.Lcf_skip_6_2:
	v_fma_f32 v26, v124, v26, v125
	s_cmp_eq_u32 s99, 14
	s_cbranch_scc0 .Lcf_skip_6_3
	s_add_u32 s100, s68, 0x1632cc40
	s_addc_u32 s101, s69, 0
	global_store_dword v21, v26, s[100:101]
.Lcf_skip_6_3:
	v_fma_f32 v26, v126, v26, v127
	s_cmp_eq_u32 s99, 13
	s_cbranch_scc0 .Lcf_skip_6_4
	s_add_u32 s100, s68, 0x1632bc40
	s_addc_u32 s101, s69, 0
	global_store_dword v21, v26, s[100:101]
.Lcf_skip_6_4:
	v_fma_f32 v26, v128, v26, v129
	s_cmp_eq_u32 s99, 12
	s_cbranch_scc0 .Lcf_skip_6_5
	s_add_u32 s100, s68, 0x1632ac40
	s_addc_u32 s101, s69, 0
	global_store_dword v21, v26, s[100:101]
.Lcf_skip_6_5:
	v_fma_f32 v26, v130, v26, v131
	s_cmp_eq_u32 s99, 11
	s_cbranch_scc0 .Lcf_skip_6_6
	s_add_u32 s100, s68, 0x16329c40
	s_addc_u32 s101, s69, 0
	global_store_dword v21, v26, s[100:101]
.Lcf_skip_6_6:
	v_fma_f32 v26, v132, v26, v133
	s_cmp_eq_u32 s99, 10
	s_cbranch_scc0 .Lcf_skip_6_7
	s_add_u32 s100, s68, 0x16328c40
	s_addc_u32 s101, s69, 0
	global_store_dword v21, v26, s[100:101]
.Lcf_skip_6_7:
	v_fma_f32 v26, v134, v26, v135
	s_cmp_eq_u32 s99, 9
	s_cbranch_scc0 .Lcf_skip_6_8
	s_add_u32 s100, s68, 0x16327c40
	s_addc_u32 s101, s69, 0
	global_store_dword v21, v26, s[100:101]

.Lcf_var_7:
	s_add_u32 s100, s68, 0x161a8c40
	s_addc_u32 s101, s69, 0
	global_load_dwordx2 v[120:121], v20, s[100:101] sc1
	s_add_u32 s100, s68, 0x161a6c40
	s_addc_u32 s101, s69, 0
	global_load_dwordx2 v[122:123], v20, s[100:101] sc1
	s_add_u32 s100, s68, 0x161a4c40
	s_addc_u32 s101, s69, 0
	global_load_dwordx2 v[124:125], v20, s[100:101] sc1
	s_add_u32 s100, s68, 0x161a2c40
	s_addc_u32 s101, s69, 0
	global_load_dwordx2 v[126:127], v20, s[100:101] sc1
	s_add_u32 s100, s68, 0x161a0c40
	s_addc_u32 s101, s69, 0
	global_load_dwordx2 v[128:129], v20, s[100:101] sc1
	s_add_u32 s100, s68, 0x1619ec40
	s_addc_u32 s101, s69, 0
	global_load_dwordx2 v[130:131], v20, s[100:101] sc1
	s_add_u32 s100, s68, 0x1619cc40
	s_addc_u32 s101, s69, 0
	global_load_dwordx2 v[132:133], v20, s[100:101] sc1
	s_add_u32 s100, s68, 0x1619ac40
	s_addc_u32 s101, s69, 0
	global_load_dwordx2 v[134:135], v20, s[100:101] sc1
	s_add_u32 s100, s68, 0x16198c40
	s_addc_u32 s101, s69, 0
	global_load_dwordx2 v[64:65], v20, s[100:101] sc1
	s_add_u32 s100, s68, 0x16196c40
	s_addc_u32 s101, s69, 0
	global_load_dwordx2 v[66:67], v20, s[100:101] sc1
	s_add_u32 s100, s68, 0x16194c40
	s_addc_u32 s101, s69, 0
	global_load_dwordx2 v[68:69], v20, s[100:101] sc1
	s_add_u32 s100, s68, 0x16192c40
	s_addc_u32 s101, s69, 0
	global_load_dwordx2 v[70:71], v20, s[100:101] sc1
	s_add_u32 s100, s68, 0x16190c40
	s_addc_u32 s101, s69, 0
	global_load_dwordx2 v[78:79], v20, s[100:101] sc1
	s_add_u32 s100, s68, 0x1618ec40
	s_addc_u32 s101, s69, 0
	global_load_dwordx2 v[80:81], v20, s[100:101] sc1
	s_add_u32 s100, s68, 0x1618cc40
	s_addc_u32 s101, s69, 0
	global_load_dwordx2 v[82:83], v20, s[100:101] sc1
	s_add_u32 s100, s68, 0x1618ac40
	s_addc_u32 s101, s69, 0
	global_load_dwordx2 v[84:85], v20, s[100:101] sc1
	s_add_u32 s100, s68, 0x16188c40
	s_addc_u32 s101, s69, 0
	global_load_dwordx2 v[86:87], v20, s[100:101] sc1
	s_add_u32 s100, s68, 0x16186c40
	s_addc_u32 s101, s69, 0
	global_load_dwordx2 v[88:89], v20, s[100:101] sc1
	s_add_u32 s100, s68, 0x16184c40
	s_addc_u32 s101, s69, 0
	global_load_dwordx2 v[90:91], v20, s[100:101] sc1
	s_add_u32 s100, s68, 0x16182c40
	s_addc_u32 s101, s69, 0
	global_load_dwordx2 v[92:93], v20, s[100:101] sc1
	s_add_u32 s100, s68, 0x16180c40
	s_addc_u32 s101, s69, 0
	global_load_dwordx2 v[94:95], v20, s[100:101] sc1
	s_add_u32 s100, s68, 0x1617ec40
	s_addc_u32 s101, s69, 0
	global_load_dwordx2 v[96:97], v20, s[100:101] sc1
	s_add_u32 s100, s68, 0x1617cc40
	s_addc_u32 s101, s69, 0
	global_load_dwordx2 v[98:99], v20, s[100:101] sc1
	s_add_u32 s100, s68, 0x1617ac40
	s_addc_u32 s101, s69, 0
	global_load_dwordx2 v[100:101], v20, s[100:101] sc1
	s_add_u32 s100, s68, 0x16178c40
	s_addc_u32 s101, s69, 0
	global_load_dwordx2 v[102:103], v20, s[100:101] sc1
	s_add_u32 s100, s68, 0x16176c40
	s_addc_u32 s101, s69, 0
	global_load_dwordx2 v[104:105], v20, s[100:101] sc1
	s_add_u32 s100, s68, 0x16174c40
	s_addc_u32 s101, s69, 0
	global_load_dwordx2 v[106:107], v20, s[100:101] sc1
	s_add_u32 s100, s68, 0x16172c40
	s_addc_u32 s101, s69, 0
	global_load_dwordx2 v[108:109], v20, s[100:101] sc1
	s_add_u32 s100, s68, 0x16170c40
	s_addc_u32 s101, s69, 0
	global_load_dwordx2 v[110:111], v20, s[100:101] sc1
	s_add_u32 s100, s68, 0x1616ec40
	s_addc_u32 s101, s69, 0
	global_load_dwordx2 v[112:113], v20, s[100:101] sc1
	s_add_u32 s100, s68, 0x1616cc40
	s_addc_u32 s101, s69, 0
	global_load_dwordx2 v[114:115], v20, s[100:101] sc1
	s_branch .Lcf_ret1
.Lcf_scan_7:
	v_mov_b32_e32 v24, 1.0
	v_mov_b32_e32 v25, 0
	s_waitcnt vmcnt(30)
	v_fma_f32 v25, v120, v25, v121
	v_mul_f32_e32 v24, v24, v120
	s_waitcnt vmcnt(29)
	v_fma_f32 v25, v122, v25, v123
	v_mul_f32_e32 v24, v24, v122
	s_waitcnt vmcnt(28)
	v_fma_f32 v25, v124, v25, v125
	v_mul_f32_e32 v24, v24, v124
	s_waitcnt vmcnt(27)
	v_fma_f32 v25, v126, v25, v127
	v_mul_f32_e32 v24, v24, v126
	s_waitcnt vmcnt(26)
	v_fma_f32 v25, v128, v25, v129
	v_mul_f32_e32 v24, v24, v128
	s_waitcnt vmcnt(25)
	v_fma_f32 v25, v130, v25, v131
	v_mul_f32_e32 v24, v24, v130
	s_waitcnt vmcnt(24)
	v_fma_f32 v25, v132, v25, v133
	v_mul_f32_e32 v24, v24, v132
	s_waitcnt vmcnt(23)
	v_fma_f32 v25, v134, v25, v135
	v_mul_f32_e32 v24, v24, v134
	s_waitcnt vmcnt(22)
	v_fma_f32 v25, v64, v25, v65
	v_mul_f32_e32 v24, v24, v64
	s_waitcnt vmcnt(21)
	v_fma_f32 v25, v66, v25, v67
	v_mul_f32_e32 v24, v24, v66
	s_waitcnt vmcnt(20)
	v_fma_f32 v25, v68, v25, v69
	v_mul_f32_e32 v24, v24, v68
	s_waitcnt vmcnt(19)
	v_fma_f32 v25, v70, v25, v71
	v_mul_f32_e32 v24, v24, v70
	s_waitcnt vmcnt(18)
	v_fma_f32 v25, v78, v25, v79
	v_mul_f32_e32 v24, v24, v78
	s_waitcnt vmcnt(17)
	v_fma_f32 v25, v80, v25, v81
	v_mul_f32_e32 v24, v24, v80
	s_waitcnt vmcnt(16)
	v_fma_f32 v25, v82, v25, v83
	v_mul_f32_e32 v24, v24, v82
	s_waitcnt vmcnt(15)
	v_fma_f32 v25, v84, v25, v85
	v_mul_f32_e32 v24, v24, v84
	s_waitcnt vmcnt(14)
	v_fma_f32 v25, v86, v25, v87
	v_mul_f32_e32 v24, v24, v86
	s_waitcnt vmcnt(13)
	v_fma_f32 v25, v88, v25, v89
	v_mul_f32_e32 v24, v24, v88
	s_waitcnt vmcnt(12)
	v_fma_f32 v25, v90, v25, v91
	v_mul_f32_e32 v24, v24, v90
	s_waitcnt vmcnt(11)
	v_fma_f32 v25, v92, v25, v93
	v_mul_f32_e32 v24, v24, v92
	s_waitcnt vmcnt(10)
	v_fma_f32 v25, v94, v25, v95
	v_mul_f32_e32 v24, v24, v94
	s_waitcnt vmcnt(9)
	v_fma_f32 v25, v96, v25, v97
	v_mul_f32_e32 v24, v24, v96
	s_waitcnt vmcnt(8)
	v_fma_f32 v25, v98, v25, v99
	v_mul_f32_e32 v24, v24, v98
	s_waitcnt vmcnt(7)
	v_fma_f32 v25, v100, v25, v101
	v_mul_f32_e32 v24, v24, v100
	s_waitcnt vmcnt(6)
	v_fma_f32 v25, v102, v25, v103
	v_mul_f32_e32 v24, v24, v102
	s_waitcnt vmcnt(5)
	v_fma_f32 v25, v104, v25, v105
	v_mul_f32_e32 v24, v24, v104
	s_waitcnt vmcnt(4)
	v_fma_f32 v25, v106, v25, v107
	v_mul_f32_e32 v24, v24, v106
	s_waitcnt vmcnt(3)
	v_fma_f32 v25, v108, v25, v109
	v_mul_f32_e32 v24, v24, v108
	s_waitcnt vmcnt(2)
	v_fma_f32 v25, v110, v25, v111
	v_mul_f32_e32 v24, v24, v110
	s_waitcnt vmcnt(1)
	v_fma_f32 v25, v112, v25, v113
	v_mul_f32_e32 v24, v24, v112
	s_waitcnt vmcnt(0)
	v_fma_f32 v25, v114, v25, v115
	v_mul_f32_e32 v24, v24, v114
	ds_write_b64 v22, v[24:25] offset:3584
	s_waitcnt lgkmcnt(0)
	s_barrier
	v_mov_b32_e32 v26, 0
	ds_read_b64 v[28:29], v22 offset:2048
	s_waitcnt lgkmcnt(0)
	v_fma_f32 v26, v28, v26, v29
	ds_read_b64 v[28:29], v22 offset:2560
	s_waitcnt lgkmcnt(0)
	v_fma_f32 v26, v28, v26, v29
	ds_read_b64 v[28:29], v22 offset:3072
	s_waitcnt lgkmcnt(0)
	v_fma_f32 v26, v28, v26, v29
	s_cmp_eq_u32 s99, 0
	s_cbranch_scc0 .Lcf_skip_7_0
	s_add_u32 s100, s68, 0x1630ec40
	s_addc_u32 s101, s69, 0
	global_store_dword v21, v26, s[100:101]
.Lcf_skip_7_0:
	v_fma_f32 v26, v120, v26, v121
	s_cmp_eq_u32 s99, 15
	s_cbranch_scc0 .Lcf_skip_7_1
	s_add_u32 s100, s68, 0x1630dc40
	s_addc_u32 s101, s69, 0
	global_store_dword v21, v26, s[100:101]
.Lcf_skip_7_1:
	v_fma_f32 v26, v122, v26, v123
	s_cmp_eq_u32 s99, 14
	s_cbranch_scc0 .Lcf_skip_7_2
	s_add_u32 s100, s68, 0x1630cc40
	s_addc_u32 s101, s69, 0
	global_store_dword v21, v26, s[100:101]
.Lcf_skip_7_2:
	v_fma_f32 v26, v124, v26, v125
	s_cmp_eq_u32 s99, 13
	s_cbranch_scc0 .Lcf_skip_7_3
	s_add_u32 s100, s68, 0x1630bc40
	s_addc_u32 s101, s69, 0
	global_store_dword v21, v26, s[100:101]
.Lcf_skip_7_3:
	v_fma_f32 v26, v126, v26, v127
	s_cmp_eq_u32 s99, 12
	s_cbranch_scc0 .Lcf_skip_7_4
	s_add_u32 s100, s68, 0x1630ac40
	s_addc_u32 s101, s69, 0
	global_store_dword v21, v26, s[100:101]
.Lcf_skip_7_4:
	v_fma_f32 v26, v128, v26, v129
	s_cmp_eq_u32 s99, 11
	s_cbranch_scc0 .Lcf_skip_7_5
	s_add_u32 s100, s68, 0x16309c40
	s_addc_u32 s101, s69, 0
	global_store_dword v21, v26, s[100:101]
.Lcf_skip_7_5:
	v_fma_f32 v26, v130, v26, v131
	s_cmp_eq_u32 s99, 10
	s_cbranch_scc0 .Lcf_skip_7_6
	s_add_u32 s100, s68, 0x16308c40
	s_addc_u32 s101, s69, 0
	global_store_dword v21, v26, s[100:101]
.Lcf_skip_7_6:
	v_fma_f32 v26, v132, v26, v133
	s_cmp_eq_u32 s99, 9
	s_cbranch_scc0 .Lcf_skip_7_7
	s_add_u32 s100, s68, 0x16307c40
	s_addc_u32 s101, s69, 0
	global_store_dword v21, v26, s[100:101]
.Lcf_skip_7_7:
	v_fma_f32 v26, v134, v26, v135
	s_cmp_eq_u32 s99, 8
	s_cbranch_scc0 .Lcf_skip_7_8
	s_add_u32 s100, s68, 0x16306c40
	s_addc_u32 s101, s69, 0
	global_store_dword v21, v26, s[100:101]

.Lcf_entry2:
	v_lshrrev_b32_e32 v23, 6, v175
	s_nop 1
	v_readfirstlane_b32 s98, v23
	s_nop 3
	s_cmp_eq_u32 s98, 1
	s_cbranch_scc1 .Lcf_scan_1
	s_cmp_eq_u32 s98, 2
	s_cbranch_scc1 .Lcf_scan_2
	s_cmp_eq_u32 s98, 3
	s_cbranch_scc1 .Lcf_scan_3
	s_cmp_eq_u32 s98, 4
	s_cbranch_scc1 .Lcf_scan_4
	s_cmp_eq_u32 s98, 5
	s_cbranch_scc1 .Lcf_scan_5
	s_cmp_eq_u32 s98, 6
	s_cbranch_scc1 .Lcf_scan_6
	s_cmp_eq_u32 s98, 7
	s_cbranch_scc1 .Lcf_scan_7
	s_branch .Lcf_scan_0
